# v20 + LDS-DMA in saddr+voffset form in six K-loops (8 fewer 64-bit VALU address adds per 2 K-tiles per wave)
# speedup vs baseline: 1.0054x; 1.0021x over previous
.LBB0_134:
	ds_read_b128 v[148:151], v156
	ds_read_b128 v[160:163], v156 offset:1024
	ds_read_b128 v[164:167], v156 offset:2048
	ds_read_b128 v[168:171], v156 offset:3072
	ds_read_b128 v[172:175], v157
	ds_read_b128 v[176:179], v157 offset:1024
	ds_read_b128 v[180:183], v157 offset:2048
	ds_read_b128 v[184:187], v157 offset:3072
	s_add_u32 s0, s34, 0xfff00080
	s_addc_u32 s1, s35, -1
	s_cmp_eq_u32 s60, 60
	s_cselect_b32 s39, s12, s1
	s_cselect_b32 s38, s13, s0
	s_cselect_b32 s37, s15, s59
	s_cselect_b32 s36, s57, s58
	s_add_i32 m0, s29, 0xc000
	ds_read_b128 v[188:191], v158
	ds_read_b128 v[192:195], v158 offset:1024
	ds_read_b128 v[196:199], v158 offset:2048
	ds_read_b128 v[200:203], v158 offset:3072
	ds_read_b128 v[208:211], v158 offset:4096
	ds_read_b128 v[212:215], v158 offset:5120
	ds_read_b128 v[216:219], v158 offset:6144
	ds_read_b128 v[220:223], v158 offset:7168
	global_load_lds_dwordx4 v140, s[34:35]
	s_add_i32 m0, s29, 0xe000
	s_nop 0
	global_load_lds_dwordx4 v142, s[34:35]
	s_waitcnt vmcnt(8)
	s_waitcnt lgkmcnt(0)
	s_setprio 3
	s_barrier
	v_mfma_f32_16x16x32_bf16 v[124:127], v[148:151], v[188:191], v[124:127]
	v_mfma_f32_16x16x32_bf16 v[120:123], v[164:167], v[188:191], v[120:123]
	v_mfma_f32_16x16x32_bf16 v[108:111], v[148:151], v[196:199], v[108:111]
	v_mfma_f32_16x16x32_bf16 v[104:107], v[164:167], v[196:199], v[104:107]
	v_mfma_f32_16x16x32_bf16 v[92:95], v[148:151], v[208:211], v[92:95]
	v_mfma_f32_16x16x32_bf16 v[88:91], v[164:167], v[208:211], v[88:91]
	v_mfma_f32_16x16x32_bf16 v[76:79], v[148:151], v[216:219], v[76:79]
	v_mfma_f32_16x16x32_bf16 v[72:75], v[164:167], v[216:219], v[72:75]
	v_mfma_f32_16x16x32_bf16 v[124:127], v[160:163], v[192:195], v[124:127]
	v_mfma_f32_16x16x32_bf16 v[120:123], v[168:171], v[192:195], v[120:123]
	v_mfma_f32_16x16x32_bf16 v[108:111], v[160:163], v[200:203], v[108:111]
	v_mfma_f32_16x16x32_bf16 v[104:107], v[168:171], v[200:203], v[104:107]
	v_mfma_f32_16x16x32_bf16 v[92:95], v[160:163], v[212:215], v[92:95]
	v_mfma_f32_16x16x32_bf16 v[88:91], v[168:171], v[212:215], v[88:91]
	v_mfma_f32_16x16x32_bf16 v[76:79], v[160:163], v[220:223], v[76:79]
	v_mfma_f32_16x16x32_bf16 v[72:75], v[168:171], v[220:223], v[72:75]
	s_setprio 0
	s_setprio 3
	v_mfma_f32_16x16x32_bf16 v[116:119], v[172:175], v[188:191], v[116:119]
	v_mfma_f32_16x16x32_bf16 v[112:115], v[180:183], v[188:191], v[112:115]
	v_mfma_f32_16x16x32_bf16 v[100:103], v[172:175], v[196:199], v[100:103]
	v_mfma_f32_16x16x32_bf16 v[96:99], v[180:183], v[196:199], v[96:99]
	v_mfma_f32_16x16x32_bf16 v[84:87], v[172:175], v[208:211], v[84:87]
	v_mfma_f32_16x16x32_bf16 v[80:83], v[180:183], v[208:211], v[80:83]
	v_mfma_f32_16x16x32_bf16 v[68:71], v[172:175], v[216:219], v[68:71]
	v_mfma_f32_16x16x32_bf16 v[64:67], v[180:183], v[216:219], v[64:67]
	v_mfma_f32_16x16x32_bf16 v[116:119], v[176:179], v[192:195], v[116:119]
	v_mfma_f32_16x16x32_bf16 v[112:115], v[184:187], v[192:195], v[112:115]
	v_mfma_f32_16x16x32_bf16 v[100:103], v[176:179], v[200:203], v[100:103]
	v_mfma_f32_16x16x32_bf16 v[96:99], v[184:187], v[200:203], v[96:99]
	v_mfma_f32_16x16x32_bf16 v[84:87], v[176:179], v[212:215], v[84:87]
	v_mfma_f32_16x16x32_bf16 v[80:83], v[184:187], v[212:215], v[80:83]
	v_mfma_f32_16x16x32_bf16 v[68:71], v[176:179], v[220:223], v[68:71]
	v_mfma_f32_16x16x32_bf16 v[64:67], v[184:187], v[220:223], v[64:67]
	s_barrier
	s_setprio 0
	s_add_i32 s0, s51, s41
	v_lshl_add_u64 v[204:205], s[36:37], 0, v[132:133]
	s_mov_b32 m0, s0
	ds_read_b128 v[188:191], v158 offset:16384
	ds_read_b128 v[192:195], v158 offset:17408
	ds_read_b128 v[196:199], v158 offset:18432
	ds_read_b128 v[200:203], v158 offset:19456
	ds_read_b128 v[208:211], v158 offset:20480
	ds_read_b128 v[212:215], v158 offset:21504
	ds_read_b128 v[216:219], v158 offset:22528
	ds_read_b128 v[220:223], v158 offset:23552
	global_load_lds_dwordx4 v[204:205], off
	s_add_i32 m0, s0, 0x2000
	s_add_u32 s62, s36, 0x100000
	v_lshl_add_u64 v[206:207], s[36:37], 0, v[136:137]
	s_addc_u32 s63, s37, 0
	s_add_i32 s0, s52, s41
	global_load_lds_dwordx4 v[206:207], off
	s_mov_b32 m0, s0
	v_lshl_add_u64 v[226:227], s[38:39], 0, v[134:135]
	global_load_lds_dwordx4 v132, s[62:63]
	s_add_i32 m0, s0, 0x2000
	s_nop 0
	global_load_lds_dwordx4 v136, s[62:63]
	v_lshl_add_u64 v[224:225], s[38:39], 0, v[130:131]
	s_mov_b32 m0, s29
	s_nop 0
	global_load_lds_dwordx4 v[224:225], off
	s_mov_b32 m0, s31
	s_nop 0
	global_load_lds_dwordx4 v[226:227], off
	s_waitcnt vmcnt(8)
	s_waitcnt lgkmcnt(0)
	s_setprio 3
	s_barrier
	v_mfma_f32_16x16x32_bf16 v[60:63], v[148:151], v[188:191], v[60:63]
	v_mfma_f32_16x16x32_bf16 v[56:59], v[164:167], v[188:191], v[56:59]
	v_mfma_f32_16x16x32_bf16 v[44:47], v[148:151], v[196:199], v[44:47]
	v_mfma_f32_16x16x32_bf16 v[40:43], v[164:167], v[196:199], v[40:43]
	v_mfma_f32_16x16x32_bf16 v[28:31], v[148:151], v[208:211], v[28:31]
	v_mfma_f32_16x16x32_bf16 v[24:27], v[164:167], v[208:211], v[24:27]
	v_mfma_f32_16x16x32_bf16 v[12:15], v[148:151], v[216:219], v[12:15]
	v_mfma_f32_16x16x32_bf16 v[8:11], v[164:167], v[216:219], v[8:11]
	v_mfma_f32_16x16x32_bf16 v[60:63], v[160:163], v[192:195], v[60:63]
	v_mfma_f32_16x16x32_bf16 v[56:59], v[168:171], v[192:195], v[56:59]
	v_mfma_f32_16x16x32_bf16 v[44:47], v[160:163], v[200:203], v[44:47]
	v_mfma_f32_16x16x32_bf16 v[40:43], v[168:171], v[200:203], v[40:43]
	v_mfma_f32_16x16x32_bf16 v[28:31], v[160:163], v[212:215], v[28:31]
	v_mfma_f32_16x16x32_bf16 v[24:27], v[168:171], v[212:215], v[24:27]
	v_mfma_f32_16x16x32_bf16 v[12:15], v[160:163], v[220:223], v[12:15]
	v_mfma_f32_16x16x32_bf16 v[8:11], v[168:171], v[220:223], v[8:11]
	s_setprio 0
	s_setprio 3
	v_mfma_f32_16x16x32_bf16 v[52:55], v[172:175], v[188:191], v[52:55]
	v_mfma_f32_16x16x32_bf16 v[48:51], v[180:183], v[188:191], v[48:51]
	v_mfma_f32_16x16x32_bf16 v[36:39], v[172:175], v[196:199], v[36:39]
	v_mfma_f32_16x16x32_bf16 v[32:35], v[180:183], v[196:199], v[32:35]
	v_mfma_f32_16x16x32_bf16 v[20:23], v[172:175], v[208:211], v[20:23]
	v_mfma_f32_16x16x32_bf16 v[16:19], v[180:183], v[208:211], v[16:19]
	v_mfma_f32_16x16x32_bf16 v[4:7], v[172:175], v[216:219], v[4:7]
	v_mfma_f32_16x16x32_bf16 v[0:3], v[180:183], v[216:219], v[0:3]
	v_mfma_f32_16x16x32_bf16 v[52:55], v[176:179], v[192:195], v[52:55]
	v_mfma_f32_16x16x32_bf16 v[48:51], v[184:187], v[192:195], v[48:51]
	v_mfma_f32_16x16x32_bf16 v[36:39], v[176:179], v[200:203], v[36:39]
	v_mfma_f32_16x16x32_bf16 v[32:35], v[184:187], v[200:203], v[32:35]
	v_mfma_f32_16x16x32_bf16 v[20:23], v[176:179], v[212:215], v[20:23]
	v_mfma_f32_16x16x32_bf16 v[16:19], v[184:187], v[212:215], v[16:19]
	v_mfma_f32_16x16x32_bf16 v[4:7], v[176:179], v[220:223], v[4:7]
	v_mfma_f32_16x16x32_bf16 v[0:3], v[184:187], v[220:223], v[0:3]
	s_barrier
	s_setprio 0
	s_add_i32 s0, 0, 0x18000
	v_add_u32_e32 v128, s0, v153
	s_add_i32 s1, 0, 0x1c000
	ds_read_b128 v[148:151], v128
	ds_read_b128 v[160:163], v128 offset:1024
	ds_read_b128 v[164:167], v128 offset:2048
	ds_read_b128 v[168:171], v128 offset:3072
	v_add_u32_e32 v128, s1, v153
	ds_read_b128 v[172:175], v128
	ds_read_b128 v[176:179], v128 offset:1024
	ds_read_b128 v[180:183], v128 offset:2048
	ds_read_b128 v[184:187], v128 offset:3072
	s_add_u32 s38, s38, 0x100000
	s_addc_u32 s39, s39, 0
	s_mov_b32 m0, s42
	ds_read_b128 v[188:191], v158 offset:32768
	ds_read_b128 v[192:195], v158 offset:33792
	ds_read_b128 v[196:199], v158 offset:34816
	ds_read_b128 v[200:203], v158 offset:35840
	ds_read_b128 v[208:211], v158 offset:36864
	ds_read_b128 v[212:215], v158 offset:37888
	ds_read_b128 v[216:219], v158 offset:38912
	ds_read_b128 v[220:223], v158 offset:39936
	global_load_lds_dwordx4 v130, s[38:39]
	s_mov_b32 m0, s43
	s_nop 0
	global_load_lds_dwordx4 v134, s[38:39]
	s_waitcnt vmcnt(8)
	s_waitcnt lgkmcnt(0)
	s_setprio 3
	s_barrier
	v_mfma_f32_16x16x32_bf16 v[124:127], v[148:151], v[188:191], v[124:127]
	v_mfma_f32_16x16x32_bf16 v[120:123], v[164:167], v[188:191], v[120:123]
	v_mfma_f32_16x16x32_bf16 v[108:111], v[148:151], v[196:199], v[108:111]
	v_mfma_f32_16x16x32_bf16 v[104:107], v[164:167], v[196:199], v[104:107]
	v_mfma_f32_16x16x32_bf16 v[92:95], v[148:151], v[208:211], v[92:95]
	v_mfma_f32_16x16x32_bf16 v[88:91], v[164:167], v[208:211], v[88:91]
	v_mfma_f32_16x16x32_bf16 v[76:79], v[148:151], v[216:219], v[76:79]
	v_mfma_f32_16x16x32_bf16 v[72:75], v[164:167], v[216:219], v[72:75]
	v_mfma_f32_16x16x32_bf16 v[124:127], v[160:163], v[192:195], v[124:127]
	v_mfma_f32_16x16x32_bf16 v[120:123], v[168:171], v[192:195], v[120:123]
	v_mfma_f32_16x16x32_bf16 v[108:111], v[160:163], v[200:203], v[108:111]
	v_mfma_f32_16x16x32_bf16 v[104:107], v[168:171], v[200:203], v[104:107]
	v_mfma_f32_16x16x32_bf16 v[92:95], v[160:163], v[212:215], v[92:95]
	v_mfma_f32_16x16x32_bf16 v[88:91], v[168:171], v[212:215], v[88:91]
	v_mfma_f32_16x16x32_bf16 v[76:79], v[160:163], v[220:223], v[76:79]
	v_mfma_f32_16x16x32_bf16 v[72:75], v[168:171], v[220:223], v[72:75]
	s_setprio 0
	s_setprio 3
	v_mfma_f32_16x16x32_bf16 v[116:119], v[172:175], v[188:191], v[116:119]
	v_mfma_f32_16x16x32_bf16 v[112:115], v[180:183], v[188:191], v[112:115]
	v_mfma_f32_16x16x32_bf16 v[100:103], v[172:175], v[196:199], v[100:103]
	v_mfma_f32_16x16x32_bf16 v[96:99], v[180:183], v[196:199], v[96:99]
	v_mfma_f32_16x16x32_bf16 v[84:87], v[172:175], v[208:211], v[84:87]
	v_mfma_f32_16x16x32_bf16 v[80:83], v[180:183], v[208:211], v[80:83]
	v_mfma_f32_16x16x32_bf16 v[68:71], v[172:175], v[216:219], v[68:71]
	v_mfma_f32_16x16x32_bf16 v[64:67], v[180:183], v[216:219], v[64:67]
	v_mfma_f32_16x16x32_bf16 v[116:119], v[176:179], v[192:195], v[116:119]
	v_mfma_f32_16x16x32_bf16 v[112:115], v[184:187], v[192:195], v[112:115]
	v_mfma_f32_16x16x32_bf16 v[100:103], v[176:179], v[200:203], v[100:103]
	v_mfma_f32_16x16x32_bf16 v[96:99], v[184:187], v[200:203], v[96:99]
	v_mfma_f32_16x16x32_bf16 v[84:87], v[176:179], v[212:215], v[84:87]
	v_mfma_f32_16x16x32_bf16 v[80:83], v[184:187], v[212:215], v[80:83]
	v_mfma_f32_16x16x32_bf16 v[68:71], v[176:179], v[220:223], v[68:71]
	v_mfma_f32_16x16x32_bf16 v[64:67], v[184:187], v[220:223], v[64:67]
	s_barrier
	s_setprio 0
	s_add_i32 s0, s0, s41
	v_lshl_add_u64 v[204:205], v[204:205], 0, s[8:9]
	s_mov_b32 m0, s0
	ds_read_b128 v[188:191], v158 offset:49152
	ds_read_b128 v[192:195], v158 offset:50176
	ds_read_b128 v[196:199], v158 offset:51200
	ds_read_b128 v[200:203], v158 offset:52224
	ds_read_b128 v[208:211], v158 offset:53248
	ds_read_b128 v[212:215], v158 offset:54272
	ds_read_b128 v[216:219], v158 offset:55296
	ds_read_b128 v[220:223], v158 offset:56320
	global_load_lds_dwordx4 v[204:205], off
	s_add_i32 m0, s0, 0x2000
	s_add_u32 s36, s36, 0x100080
	v_lshl_add_u64 v[204:205], v[206:207], 0, s[8:9]
	s_addc_u32 s37, s37, 0
	s_add_i32 s0, s1, s41
	global_load_lds_dwordx4 v[204:205], off
	s_mov_b32 m0, s0
	s_nop 0
	global_load_lds_dwordx4 v132, s[36:37]
	s_add_i32 m0, s0, 0x2000
	s_nop 0
	global_load_lds_dwordx4 v136, s[36:37]
	v_lshl_add_u64 v[204:205], v[224:225], 0, s[8:9]
	s_mov_b32 m0, s46
	s_nop 0
	global_load_lds_dwordx4 v[204:205], off
	v_lshl_add_u64 v[204:205], v[226:227], 0, s[8:9]
	s_mov_b32 m0, s47
	s_nop 0
	global_load_lds_dwordx4 v[204:205], off
	s_waitcnt vmcnt(8)
	s_waitcnt lgkmcnt(0)
	s_setprio 3
	s_barrier
	v_mfma_f32_16x16x32_bf16 v[60:63], v[148:151], v[188:191], v[60:63]
	v_mfma_f32_16x16x32_bf16 v[56:59], v[164:167], v[188:191], v[56:59]
	v_mfma_f32_16x16x32_bf16 v[44:47], v[148:151], v[196:199], v[44:47]
	v_mfma_f32_16x16x32_bf16 v[40:43], v[164:167], v[196:199], v[40:43]
	v_mfma_f32_16x16x32_bf16 v[28:31], v[148:151], v[208:211], v[28:31]
	v_mfma_f32_16x16x32_bf16 v[24:27], v[164:167], v[208:211], v[24:27]
	v_mfma_f32_16x16x32_bf16 v[12:15], v[148:151], v[216:219], v[12:15]
	v_mfma_f32_16x16x32_bf16 v[8:11], v[164:167], v[216:219], v[8:11]
	v_mfma_f32_16x16x32_bf16 v[60:63], v[160:163], v[192:195], v[60:63]
	v_mfma_f32_16x16x32_bf16 v[56:59], v[168:171], v[192:195], v[56:59]
	v_mfma_f32_16x16x32_bf16 v[44:47], v[160:163], v[200:203], v[44:47]
	v_mfma_f32_16x16x32_bf16 v[40:43], v[168:171], v[200:203], v[40:43]
	v_mfma_f32_16x16x32_bf16 v[28:31], v[160:163], v[212:215], v[28:31]
	v_mfma_f32_16x16x32_bf16 v[24:27], v[168:171], v[212:215], v[24:27]
	v_mfma_f32_16x16x32_bf16 v[12:15], v[160:163], v[220:223], v[12:15]
	v_mfma_f32_16x16x32_bf16 v[8:11], v[168:171], v[220:223], v[8:11]
	s_setprio 0
	s_setprio 3
	v_mfma_f32_16x16x32_bf16 v[52:55], v[172:175], v[188:191], v[52:55]
	v_mfma_f32_16x16x32_bf16 v[48:51], v[180:183], v[188:191], v[48:51]
	v_mfma_f32_16x16x32_bf16 v[36:39], v[172:175], v[196:199], v[36:39]
	v_mfma_f32_16x16x32_bf16 v[32:35], v[180:183], v[196:199], v[32:35]
	v_mfma_f32_16x16x32_bf16 v[20:23], v[172:175], v[208:211], v[20:23]
	v_mfma_f32_16x16x32_bf16 v[16:19], v[180:183], v[208:211], v[16:19]
	v_mfma_f32_16x16x32_bf16 v[4:7], v[172:175], v[216:219], v[4:7]
	v_mfma_f32_16x16x32_bf16 v[0:3], v[180:183], v[216:219], v[0:3]
	v_mfma_f32_16x16x32_bf16 v[52:55], v[176:179], v[192:195], v[52:55]
	v_mfma_f32_16x16x32_bf16 v[48:51], v[184:187], v[192:195], v[48:51]
	v_mfma_f32_16x16x32_bf16 v[36:39], v[176:179], v[200:203], v[36:39]
	v_mfma_f32_16x16x32_bf16 v[32:35], v[184:187], v[200:203], v[32:35]
	v_mfma_f32_16x16x32_bf16 v[20:23], v[176:179], v[212:215], v[20:23]
	v_mfma_f32_16x16x32_bf16 v[16:19], v[184:187], v[212:215], v[16:19]
	v_mfma_f32_16x16x32_bf16 v[4:7], v[176:179], v[220:223], v[4:7]
	v_mfma_f32_16x16x32_bf16 v[0:3], v[184:187], v[220:223], v[0:3]
	s_barrier
	s_setprio 0
	s_add_u32 s34, s34, 0x100
	s_addc_u32 s35, s35, 0
	s_add_i32 s60, s60, 2
	s_add_u32 s58, s58, 0x100
	s_addc_u32 s59, s59, 0
	s_cmp_gt_u32 s60, 61
	s_cbranch_scc0 .LBB0_134
	s_and_b64 vcc, exec, s[10:11]
	s_cbranch_vccz .LBB0_137
	s_barrier

.LBB0_677:
	ds_read_b128 v[156:159], v152
	ds_read_b128 v[160:163], v152 offset:1024
	ds_read_b128 v[164:167], v152 offset:2048
	ds_read_b128 v[168:171], v152 offset:3072
	ds_read_b128 v[172:175], v153
	ds_read_b128 v[176:179], v153 offset:1024
	ds_read_b128 v[180:183], v153 offset:2048
	ds_read_b128 v[184:187], v153 offset:3072
	s_add_u32 s0, s36, 0xfff00080
	s_addc_u32 s1, s37, -1
	s_cmp_eq_u32 s61, 60
	s_cselect_b32 s41, s56, s1
	s_cselect_b32 s40, s57, s0
	s_cselect_b32 s39, s15, s60
	s_cselect_b32 s38, s58, s59
	s_add_i32 m0, s31, 0xc000
	ds_read_b128 v[188:191], v154
	ds_read_b128 v[192:195], v154 offset:1024
	ds_read_b128 v[196:199], v154 offset:2048
	ds_read_b128 v[200:203], v154 offset:3072
	ds_read_b128 v[204:207], v154 offset:4096
	ds_read_b128 v[208:211], v154 offset:5120
	ds_read_b128 v[212:215], v154 offset:6144
	ds_read_b128 v[216:219], v154 offset:7168
	global_load_lds_dwordx4 v138, s[36:37]
	s_add_i32 m0, s31, 0xe000
	s_nop 0
	global_load_lds_dwordx4 v140, s[36:37]
	s_waitcnt vmcnt(8)
	s_waitcnt lgkmcnt(0)
	s_setprio 3
	s_barrier
	v_mfma_f32_16x16x32_bf16 v[124:127], v[156:159], v[188:191], v[124:127]
	v_mfma_f32_16x16x32_bf16 v[120:123], v[164:167], v[188:191], v[120:123]
	v_mfma_f32_16x16x32_bf16 v[108:111], v[156:159], v[196:199], v[108:111]
	v_mfma_f32_16x16x32_bf16 v[104:107], v[164:167], v[196:199], v[104:107]
	v_mfma_f32_16x16x32_bf16 v[92:95], v[156:159], v[204:207], v[92:95]
	v_mfma_f32_16x16x32_bf16 v[88:91], v[164:167], v[204:207], v[88:91]
	v_mfma_f32_16x16x32_bf16 v[76:79], v[156:159], v[212:215], v[76:79]
	v_mfma_f32_16x16x32_bf16 v[72:75], v[164:167], v[212:215], v[72:75]
	v_mfma_f32_16x16x32_bf16 v[124:127], v[160:163], v[192:195], v[124:127]
	v_mfma_f32_16x16x32_bf16 v[120:123], v[168:171], v[192:195], v[120:123]
	v_mfma_f32_16x16x32_bf16 v[108:111], v[160:163], v[200:203], v[108:111]
	v_mfma_f32_16x16x32_bf16 v[104:107], v[168:171], v[200:203], v[104:107]
	v_mfma_f32_16x16x32_bf16 v[92:95], v[160:163], v[208:211], v[92:95]
	v_mfma_f32_16x16x32_bf16 v[88:91], v[168:171], v[208:211], v[88:91]
	v_mfma_f32_16x16x32_bf16 v[76:79], v[160:163], v[216:219], v[76:79]
	v_mfma_f32_16x16x32_bf16 v[72:75], v[168:171], v[216:219], v[72:75]
	s_setprio 0
	s_setprio 3
	v_mfma_f32_16x16x32_bf16 v[116:119], v[172:175], v[188:191], v[116:119]
	v_mfma_f32_16x16x32_bf16 v[112:115], v[180:183], v[188:191], v[112:115]
	v_mfma_f32_16x16x32_bf16 v[100:103], v[172:175], v[196:199], v[100:103]
	v_mfma_f32_16x16x32_bf16 v[96:99], v[180:183], v[196:199], v[96:99]
	v_mfma_f32_16x16x32_bf16 v[84:87], v[172:175], v[204:207], v[84:87]
	v_mfma_f32_16x16x32_bf16 v[80:83], v[180:183], v[204:207], v[80:83]
	v_mfma_f32_16x16x32_bf16 v[68:71], v[172:175], v[212:215], v[68:71]
	v_mfma_f32_16x16x32_bf16 v[64:67], v[180:183], v[212:215], v[64:67]
	v_mfma_f32_16x16x32_bf16 v[116:119], v[176:179], v[192:195], v[116:119]
	v_mfma_f32_16x16x32_bf16 v[112:115], v[184:187], v[192:195], v[112:115]
	v_mfma_f32_16x16x32_bf16 v[100:103], v[176:179], v[200:203], v[100:103]
	v_mfma_f32_16x16x32_bf16 v[96:99], v[184:187], v[200:203], v[96:99]
	v_mfma_f32_16x16x32_bf16 v[84:87], v[176:179], v[208:211], v[84:87]
	v_mfma_f32_16x16x32_bf16 v[80:83], v[184:187], v[208:211], v[80:83]
	v_mfma_f32_16x16x32_bf16 v[68:71], v[176:179], v[216:219], v[68:71]
	v_mfma_f32_16x16x32_bf16 v[64:67], v[184:187], v[216:219], v[64:67]
	s_barrier
	s_setprio 0
	s_add_i32 s0, s51, s43
	v_lshl_add_u64 v[146:147], s[38:39], 0, v[130:131]
	s_mov_b32 m0, s0
	ds_read_b128 v[188:191], v154 offset:16384
	ds_read_b128 v[192:195], v154 offset:17408
	ds_read_b128 v[196:199], v154 offset:18432
	ds_read_b128 v[200:203], v154 offset:19456
	ds_read_b128 v[204:207], v154 offset:20480
	ds_read_b128 v[208:211], v154 offset:21504
	ds_read_b128 v[212:215], v154 offset:22528
	ds_read_b128 v[216:219], v154 offset:23552
	global_load_lds_dwordx4 v[146:147], off
	s_add_i32 m0, s0, 0x2000
	s_add_u32 s0, s38, 0x100000
	v_lshl_add_u64 v[220:221], s[38:39], 0, v[134:135]
	s_addc_u32 s1, s39, 0
	s_add_i32 s62, s52, s43
	global_load_lds_dwordx4 v[220:221], off
	s_mov_b32 m0, s62
	v_lshl_add_u64 v[224:225], s[40:41], 0, v[132:133]
	global_load_lds_dwordx4 v130, s[0:1]
	s_add_i32 m0, s62, 0x2000
	s_nop 0
	global_load_lds_dwordx4 v134, s[0:1]
	v_lshl_add_u64 v[222:223], s[40:41], 0, v[128:129]
	s_mov_b32 m0, s31
	s_nop 0
	global_load_lds_dwordx4 v[222:223], off
	s_mov_b32 m0, s35
	s_nop 0
	global_load_lds_dwordx4 v[224:225], off
	s_waitcnt vmcnt(8)
	s_waitcnt lgkmcnt(0)
	s_setprio 3
	s_barrier
	v_mfma_f32_16x16x32_bf16 v[60:63], v[156:159], v[188:191], v[60:63]
	v_mfma_f32_16x16x32_bf16 v[56:59], v[164:167], v[188:191], v[56:59]
	v_mfma_f32_16x16x32_bf16 v[44:47], v[156:159], v[196:199], v[44:47]
	v_mfma_f32_16x16x32_bf16 v[40:43], v[164:167], v[196:199], v[40:43]
	v_mfma_f32_16x16x32_bf16 v[28:31], v[156:159], v[204:207], v[28:31]
	v_mfma_f32_16x16x32_bf16 v[24:27], v[164:167], v[204:207], v[24:27]
	v_mfma_f32_16x16x32_bf16 v[12:15], v[156:159], v[212:215], v[12:15]
	v_mfma_f32_16x16x32_bf16 v[8:11], v[164:167], v[212:215], v[8:11]
	v_mfma_f32_16x16x32_bf16 v[60:63], v[160:163], v[192:195], v[60:63]
	v_mfma_f32_16x16x32_bf16 v[56:59], v[168:171], v[192:195], v[56:59]
	v_mfma_f32_16x16x32_bf16 v[44:47], v[160:163], v[200:203], v[44:47]
	v_mfma_f32_16x16x32_bf16 v[40:43], v[168:171], v[200:203], v[40:43]
	v_mfma_f32_16x16x32_bf16 v[28:31], v[160:163], v[208:211], v[28:31]
	v_mfma_f32_16x16x32_bf16 v[24:27], v[168:171], v[208:211], v[24:27]
	v_mfma_f32_16x16x32_bf16 v[12:15], v[160:163], v[216:219], v[12:15]
	v_mfma_f32_16x16x32_bf16 v[8:11], v[168:171], v[216:219], v[8:11]
	s_setprio 0
	s_setprio 3
	v_mfma_f32_16x16x32_bf16 v[52:55], v[172:175], v[188:191], v[52:55]
	v_mfma_f32_16x16x32_bf16 v[48:51], v[180:183], v[188:191], v[48:51]
	v_mfma_f32_16x16x32_bf16 v[36:39], v[172:175], v[196:199], v[36:39]
	v_mfma_f32_16x16x32_bf16 v[32:35], v[180:183], v[196:199], v[32:35]
	v_mfma_f32_16x16x32_bf16 v[20:23], v[172:175], v[204:207], v[20:23]
	v_mfma_f32_16x16x32_bf16 v[16:19], v[180:183], v[204:207], v[16:19]
	v_mfma_f32_16x16x32_bf16 v[4:7], v[172:175], v[212:215], v[4:7]
	v_mfma_f32_16x16x32_bf16 v[0:3], v[180:183], v[212:215], v[0:3]
	v_mfma_f32_16x16x32_bf16 v[52:55], v[176:179], v[192:195], v[52:55]
	v_mfma_f32_16x16x32_bf16 v[48:51], v[184:187], v[192:195], v[48:51]
	v_mfma_f32_16x16x32_bf16 v[36:39], v[176:179], v[200:203], v[36:39]
	v_mfma_f32_16x16x32_bf16 v[32:35], v[184:187], v[200:203], v[32:35]
	v_mfma_f32_16x16x32_bf16 v[20:23], v[176:179], v[208:211], v[20:23]
	v_mfma_f32_16x16x32_bf16 v[16:19], v[184:187], v[208:211], v[16:19]
	v_mfma_f32_16x16x32_bf16 v[4:7], v[176:179], v[216:219], v[4:7]
	v_mfma_f32_16x16x32_bf16 v[0:3], v[184:187], v[216:219], v[0:3]
	s_barrier
	s_setprio 0
	s_add_i32 s62, 0, 0x18000
	v_add_u32_e32 v155, s62, v149
	s_add_i32 s63, 0, 0x1c000
	ds_read_b128 v[156:159], v155
	ds_read_b128 v[160:163], v155 offset:1024
	ds_read_b128 v[164:167], v155 offset:2048
	ds_read_b128 v[168:171], v155 offset:3072
	v_add_u32_e32 v155, s63, v149
	ds_read_b128 v[172:175], v155
	ds_read_b128 v[176:179], v155 offset:1024
	ds_read_b128 v[180:183], v155 offset:2048
	ds_read_b128 v[184:187], v155 offset:3072
	s_add_u32 s0, s40, 0x100000
	s_addc_u32 s1, s41, 0
	s_mov_b32 m0, s44
	ds_read_b128 v[188:191], v154 offset:32768
	ds_read_b128 v[192:195], v154 offset:33792
	ds_read_b128 v[196:199], v154 offset:34816
	ds_read_b128 v[200:203], v154 offset:35840
	ds_read_b128 v[204:207], v154 offset:36864
	ds_read_b128 v[208:211], v154 offset:37888
	ds_read_b128 v[212:215], v154 offset:38912
	ds_read_b128 v[216:219], v154 offset:39936
	global_load_lds_dwordx4 v128, s[0:1]
	s_mov_b32 m0, s45
	s_nop 0
	global_load_lds_dwordx4 v132, s[0:1]
	s_waitcnt vmcnt(8)
	s_waitcnt lgkmcnt(0)
	s_setprio 3
	s_barrier
	v_mfma_f32_16x16x32_bf16 v[124:127], v[156:159], v[188:191], v[124:127]
	v_mfma_f32_16x16x32_bf16 v[120:123], v[164:167], v[188:191], v[120:123]
	v_mfma_f32_16x16x32_bf16 v[108:111], v[156:159], v[196:199], v[108:111]
	v_mfma_f32_16x16x32_bf16 v[104:107], v[164:167], v[196:199], v[104:107]
	v_mfma_f32_16x16x32_bf16 v[92:95], v[156:159], v[204:207], v[92:95]
	v_mfma_f32_16x16x32_bf16 v[88:91], v[164:167], v[204:207], v[88:91]
	v_mfma_f32_16x16x32_bf16 v[76:79], v[156:159], v[212:215], v[76:79]
	v_mfma_f32_16x16x32_bf16 v[72:75], v[164:167], v[212:215], v[72:75]
	v_mfma_f32_16x16x32_bf16 v[124:127], v[160:163], v[192:195], v[124:127]
	v_mfma_f32_16x16x32_bf16 v[120:123], v[168:171], v[192:195], v[120:123]
	v_mfma_f32_16x16x32_bf16 v[108:111], v[160:163], v[200:203], v[108:111]
	v_mfma_f32_16x16x32_bf16 v[104:107], v[168:171], v[200:203], v[104:107]
	v_mfma_f32_16x16x32_bf16 v[92:95], v[160:163], v[208:211], v[92:95]
	v_mfma_f32_16x16x32_bf16 v[88:91], v[168:171], v[208:211], v[88:91]
	v_mfma_f32_16x16x32_bf16 v[76:79], v[160:163], v[216:219], v[76:79]
	v_mfma_f32_16x16x32_bf16 v[72:75], v[168:171], v[216:219], v[72:75]
	s_setprio 0
	s_setprio 3
	v_mfma_f32_16x16x32_bf16 v[116:119], v[172:175], v[188:191], v[116:119]
	v_mfma_f32_16x16x32_bf16 v[112:115], v[180:183], v[188:191], v[112:115]
	v_mfma_f32_16x16x32_bf16 v[100:103], v[172:175], v[196:199], v[100:103]
	v_mfma_f32_16x16x32_bf16 v[96:99], v[180:183], v[196:199], v[96:99]
	v_mfma_f32_16x16x32_bf16 v[84:87], v[172:175], v[204:207], v[84:87]
	v_mfma_f32_16x16x32_bf16 v[80:83], v[180:183], v[204:207], v[80:83]
	v_mfma_f32_16x16x32_bf16 v[68:71], v[172:175], v[212:215], v[68:71]
	v_mfma_f32_16x16x32_bf16 v[64:67], v[180:183], v[212:215], v[64:67]
	v_mfma_f32_16x16x32_bf16 v[116:119], v[176:179], v[192:195], v[116:119]
	v_mfma_f32_16x16x32_bf16 v[112:115], v[184:187], v[192:195], v[112:115]
	v_mfma_f32_16x16x32_bf16 v[100:103], v[176:179], v[200:203], v[100:103]
	v_mfma_f32_16x16x32_bf16 v[96:99], v[184:187], v[200:203], v[96:99]
	v_mfma_f32_16x16x32_bf16 v[84:87], v[176:179], v[208:211], v[84:87]
	v_mfma_f32_16x16x32_bf16 v[80:83], v[184:187], v[208:211], v[80:83]
	v_mfma_f32_16x16x32_bf16 v[68:71], v[176:179], v[216:219], v[68:71]
	v_mfma_f32_16x16x32_bf16 v[64:67], v[184:187], v[216:219], v[64:67]
	s_barrier
	s_setprio 0
	s_add_i32 s0, s62, s43
	v_lshl_add_u64 v[146:147], v[146:147], 0, s[10:11]
	s_mov_b32 m0, s0
	ds_read_b128 v[188:191], v154 offset:49152
	ds_read_b128 v[192:195], v154 offset:50176
	ds_read_b128 v[196:199], v154 offset:51200
	ds_read_b128 v[200:203], v154 offset:52224
	ds_read_b128 v[204:207], v154 offset:53248
	ds_read_b128 v[208:211], v154 offset:54272
	ds_read_b128 v[212:215], v154 offset:55296
	ds_read_b128 v[216:219], v154 offset:56320
	global_load_lds_dwordx4 v[146:147], off
	s_add_i32 m0, s0, 0x2000
	s_add_u32 s0, s38, 0x100080
	v_lshl_add_u64 v[146:147], v[220:221], 0, s[10:11]
	s_addc_u32 s1, s39, 0
	s_add_i32 s38, s63, s43
	global_load_lds_dwordx4 v[146:147], off
	s_mov_b32 m0, s38
	s_nop 0
	global_load_lds_dwordx4 v130, s[0:1]
	s_add_i32 m0, s38, 0x2000
	s_nop 0
	global_load_lds_dwordx4 v134, s[0:1]
	v_lshl_add_u64 v[146:147], v[222:223], 0, s[10:11]
	s_mov_b32 m0, s46
	s_nop 0
	global_load_lds_dwordx4 v[146:147], off
	v_lshl_add_u64 v[146:147], v[224:225], 0, s[10:11]
	s_mov_b32 m0, s47
	s_nop 0
	global_load_lds_dwordx4 v[146:147], off
	s_waitcnt vmcnt(8)
	s_waitcnt lgkmcnt(0)
	s_setprio 3
	s_barrier
	v_mfma_f32_16x16x32_bf16 v[60:63], v[156:159], v[188:191], v[60:63]
	v_mfma_f32_16x16x32_bf16 v[56:59], v[164:167], v[188:191], v[56:59]
	v_mfma_f32_16x16x32_bf16 v[44:47], v[156:159], v[196:199], v[44:47]
	v_mfma_f32_16x16x32_bf16 v[40:43], v[164:167], v[196:199], v[40:43]
	v_mfma_f32_16x16x32_bf16 v[28:31], v[156:159], v[204:207], v[28:31]
	v_mfma_f32_16x16x32_bf16 v[24:27], v[164:167], v[204:207], v[24:27]
	v_mfma_f32_16x16x32_bf16 v[12:15], v[156:159], v[212:215], v[12:15]
	v_mfma_f32_16x16x32_bf16 v[8:11], v[164:167], v[212:215], v[8:11]
	v_mfma_f32_16x16x32_bf16 v[60:63], v[160:163], v[192:195], v[60:63]
	v_mfma_f32_16x16x32_bf16 v[56:59], v[168:171], v[192:195], v[56:59]
	v_mfma_f32_16x16x32_bf16 v[44:47], v[160:163], v[200:203], v[44:47]
	v_mfma_f32_16x16x32_bf16 v[40:43], v[168:171], v[200:203], v[40:43]
	v_mfma_f32_16x16x32_bf16 v[28:31], v[160:163], v[208:211], v[28:31]
	v_mfma_f32_16x16x32_bf16 v[24:27], v[168:171], v[208:211], v[24:27]
	v_mfma_f32_16x16x32_bf16 v[12:15], v[160:163], v[216:219], v[12:15]
	v_mfma_f32_16x16x32_bf16 v[8:11], v[168:171], v[216:219], v[8:11]
	s_setprio 0
	s_setprio 3
	v_mfma_f32_16x16x32_bf16 v[52:55], v[172:175], v[188:191], v[52:55]
	v_mfma_f32_16x16x32_bf16 v[48:51], v[180:183], v[188:191], v[48:51]
	v_mfma_f32_16x16x32_bf16 v[36:39], v[172:175], v[196:199], v[36:39]
	v_mfma_f32_16x16x32_bf16 v[32:35], v[180:183], v[196:199], v[32:35]
	v_mfma_f32_16x16x32_bf16 v[20:23], v[172:175], v[204:207], v[20:23]
	v_mfma_f32_16x16x32_bf16 v[16:19], v[180:183], v[204:207], v[16:19]
	v_mfma_f32_16x16x32_bf16 v[4:7], v[172:175], v[212:215], v[4:7]
	v_mfma_f32_16x16x32_bf16 v[0:3], v[180:183], v[212:215], v[0:3]
	v_mfma_f32_16x16x32_bf16 v[52:55], v[176:179], v[192:195], v[52:55]
	v_mfma_f32_16x16x32_bf16 v[48:51], v[184:187], v[192:195], v[48:51]
	v_mfma_f32_16x16x32_bf16 v[36:39], v[176:179], v[200:203], v[36:39]
	v_mfma_f32_16x16x32_bf16 v[32:35], v[184:187], v[200:203], v[32:35]
	v_mfma_f32_16x16x32_bf16 v[20:23], v[176:179], v[208:211], v[20:23]
	v_mfma_f32_16x16x32_bf16 v[16:19], v[184:187], v[208:211], v[16:19]
	v_mfma_f32_16x16x32_bf16 v[4:7], v[176:179], v[216:219], v[4:7]
	v_mfma_f32_16x16x32_bf16 v[0:3], v[184:187], v[216:219], v[0:3]
	s_barrier
	s_setprio 0
	s_add_u32 s36, s36, 0x100
	s_addc_u32 s37, s37, 0
	s_add_i32 s61, s61, 2
	s_add_u32 s59, s59, 0x100
	s_addc_u32 s60, s60, 0
	s_cmp_gt_u32 s61, 61
	s_cbranch_scc0 .LBB0_677
	s_and_b64 vcc, exec, s[12:13]
	s_cbranch_vccz .LBB0_680
	s_barrier

.LBB0_705:
	ds_read_b128 v[24:27], v191
	ds_read_b128 v[28:31], v191 offset:1024
	ds_read_b128 v[16:19], v191 offset:2048
	ds_read_b128 v[20:23], v191 offset:3072
	ds_read_b128 v[8:11], v192
	ds_read_b128 v[12:15], v192 offset:1024
	ds_read_b128 v[0:3], v192 offset:2048
	ds_read_b128 v[4:7], v192 offset:3072
	s_add_u32 s0, s44, 0xfff80080
	s_addc_u32 s1, s45, -1
	s_cmp_eq_u32 s70, 28
	s_cselect_b32 s49, s60, s1
	s_cselect_b32 s48, s66, s0
	s_cselect_b32 s47, s31, s69
	s_cselect_b32 s46, s67, s68
	s_add_i32 m0, s41, 0xc000
	ds_read_b128 v[178:181], v193
	ds_read_b128 v[182:185], v193 offset:1024
	ds_read_b128 v[194:197], v193 offset:2048
	ds_read_b128 v[198:201], v193 offset:3072
	ds_read_b128 v[208:211], v193 offset:4096
	ds_read_b128 v[212:215], v193 offset:5120
	ds_read_b128 v[216:219], v193 offset:6144
	ds_read_b128 v[220:223], v193 offset:7168
	global_load_lds_dwordx4 v170, s[44:45]
	s_add_i32 m0, s41, 0xe000
	s_nop 0
	global_load_lds_dwordx4 v172, s[44:45]
	s_waitcnt vmcnt(8)
	s_waitcnt lgkmcnt(0)
	s_setprio 3
	s_barrier
	v_mfma_scale_f32_16x16x128_f8f6f4 v[156:159], v[24:31], v[178:185], v[156:159], v186, v186 op_sel_hi:[0,0,0]
	v_mfma_scale_f32_16x16x128_f8f6f4 v[152:155], v[16:23], v[178:185], v[152:155], v186, v186 op_sel_hi:[0,0,0]
	v_mfma_scale_f32_16x16x128_f8f6f4 v[140:143], v[24:31], v[194:201], v[140:143], v186, v186 op_sel_hi:[0,0,0]
	v_mfma_scale_f32_16x16x128_f8f6f4 v[136:139], v[16:23], v[194:201], v[136:139], v186, v186 op_sel_hi:[0,0,0]
	v_mfma_scale_f32_16x16x128_f8f6f4 v[124:127], v[24:31], v[208:215], v[124:127], v186, v186 op_sel_hi:[0,0,0]
	v_mfma_scale_f32_16x16x128_f8f6f4 v[120:123], v[16:23], v[208:215], v[120:123], v186, v186 op_sel_hi:[0,0,0]
	v_mfma_scale_f32_16x16x128_f8f6f4 v[108:111], v[24:31], v[216:223], v[108:111], v186, v186 op_sel_hi:[0,0,0]
	v_mfma_scale_f32_16x16x128_f8f6f4 v[104:107], v[16:23], v[216:223], v[104:107], v186, v186 op_sel_hi:[0,0,0]
	s_setprio 0
	s_setprio 3
	v_mfma_scale_f32_16x16x128_f8f6f4 v[148:151], v[8:15], v[178:185], v[148:151], v186, v186 op_sel_hi:[0,0,0]
	v_mfma_scale_f32_16x16x128_f8f6f4 v[144:147], v[0:7], v[178:185], v[144:147], v186, v186 op_sel_hi:[0,0,0]
	v_mfma_scale_f32_16x16x128_f8f6f4 v[132:135], v[8:15], v[194:201], v[132:135], v186, v186 op_sel_hi:[0,0,0]
	v_mfma_scale_f32_16x16x128_f8f6f4 v[128:131], v[0:7], v[194:201], v[128:131], v186, v186 op_sel_hi:[0,0,0]
	v_mfma_scale_f32_16x16x128_f8f6f4 v[116:119], v[8:15], v[208:215], v[116:119], v186, v186 op_sel_hi:[0,0,0]
	v_mfma_scale_f32_16x16x128_f8f6f4 v[112:115], v[0:7], v[208:215], v[112:115], v186, v186 op_sel_hi:[0,0,0]
	v_mfma_scale_f32_16x16x128_f8f6f4 v[100:103], v[8:15], v[216:223], v[100:103], v186, v186 op_sel_hi:[0,0,0]
	v_mfma_scale_f32_16x16x128_f8f6f4 v[96:99], v[0:7], v[216:223], v[96:99], v186, v186 op_sel_hi:[0,0,0]
	s_barrier
	s_setprio 0
	s_add_i32 s0, s58, s51
	v_lshl_add_u64 v[178:179], s[46:47], 0, v[162:163]
	s_mov_b32 m0, s0
	ds_read_b128 v[194:197], v193 offset:16384
	ds_read_b128 v[198:201], v193 offset:17408
	ds_read_b128 v[208:211], v193 offset:18432
	ds_read_b128 v[212:215], v193 offset:19456
	ds_read_b128 v[216:219], v193 offset:20480
	ds_read_b128 v[220:223], v193 offset:21504
	ds_read_b128 v[224:227], v193 offset:22528
	ds_read_b128 v[228:231], v193 offset:23552
	global_load_lds_dwordx4 v[178:179], off
	s_add_i32 m0, s0, 0x2000
	s_add_u32 s0, s46, 0x80000
	v_lshl_add_u64 v[180:181], s[46:47], 0, v[166:167]
	s_addc_u32 s1, s47, 0
	s_add_i32 s71, s59, s51
	global_load_lds_dwordx4 v[180:181], off
	s_mov_b32 m0, s71
	v_lshl_add_u64 v[184:185], s[48:49], 0, v[164:165]
	global_load_lds_dwordx4 v162, s[0:1]
	s_add_i32 m0, s71, 0x2000
	s_nop 0
	global_load_lds_dwordx4 v166, s[0:1]
	v_lshl_add_u64 v[182:183], s[48:49], 0, v[160:161]
	s_mov_b32 m0, s41
	s_nop 0
	global_load_lds_dwordx4 v[182:183], off
	s_mov_b32 m0, s43
	s_nop 0
	global_load_lds_dwordx4 v[184:185], off
	s_waitcnt vmcnt(8)
	s_waitcnt lgkmcnt(0)
	s_setprio 3
	s_barrier
	v_mfma_scale_f32_16x16x128_f8f6f4 v[92:95], v[24:31], v[194:201], v[92:95], v186, v186 op_sel_hi:[0,0,0]
	v_mfma_scale_f32_16x16x128_f8f6f4 v[88:91], v[16:23], v[194:201], v[88:91], v186, v186 op_sel_hi:[0,0,0]
	v_mfma_scale_f32_16x16x128_f8f6f4 v[80:83], v[24:31], v[208:215], v[80:83], v186, v186 op_sel_hi:[0,0,0]
	v_mfma_scale_f32_16x16x128_f8f6f4 v[72:75], v[16:23], v[208:215], v[72:75], v186, v186 op_sel_hi:[0,0,0]
	v_mfma_scale_f32_16x16x128_f8f6f4 v[64:67], v[24:31], v[216:223], v[64:67], v186, v186 op_sel_hi:[0,0,0]
	v_mfma_scale_f32_16x16x128_f8f6f4 v[56:59], v[16:23], v[216:223], v[56:59], v186, v186 op_sel_hi:[0,0,0]
	v_mfma_scale_f32_16x16x128_f8f6f4 v[48:51], v[24:31], v[224:231], v[48:51], v186, v186 op_sel_hi:[0,0,0]
	v_mfma_scale_f32_16x16x128_f8f6f4 v[40:43], v[16:23], v[224:231], v[40:43], v186, v186 op_sel_hi:[0,0,0]
	s_setprio 0
	s_setprio 3
	v_mfma_scale_f32_16x16x128_f8f6f4 v[84:87], v[8:15], v[194:201], v[84:87], v186, v186 op_sel_hi:[0,0,0]
	v_mfma_scale_f32_16x16x128_f8f6f4 v[76:79], v[0:7], v[194:201], v[76:79], v186, v186 op_sel_hi:[0,0,0]
	v_mfma_scale_f32_16x16x128_f8f6f4 v[68:71], v[8:15], v[208:215], v[68:71], v186, v186 op_sel_hi:[0,0,0]
	v_mfma_scale_f32_16x16x128_f8f6f4 v[60:63], v[0:7], v[208:215], v[60:63], v186, v186 op_sel_hi:[0,0,0]
	v_mfma_scale_f32_16x16x128_f8f6f4 v[52:55], v[8:15], v[216:223], v[52:55], v186, v186 op_sel_hi:[0,0,0]
	v_mfma_scale_f32_16x16x128_f8f6f4 v[44:47], v[0:7], v[216:223], v[44:47], v186, v186 op_sel_hi:[0,0,0]
	v_mfma_scale_f32_16x16x128_f8f6f4 v[36:39], v[8:15], v[224:231], v[36:39], v186, v186 op_sel_hi:[0,0,0]
	v_mfma_scale_f32_16x16x128_f8f6f4 v[32:35], v[0:7], v[224:231], v[32:35], v186, v186 op_sel_hi:[0,0,0]
	s_barrier
	s_setprio 0
	s_add_i32 s71, 0, 0x18000
	s_add_i32 s73, 0, 0x1c000
	v_add_u32_e32 v12, s71, v188
	v_add_u32_e32 v28, s73, v188
	ds_read_b128 v[0:3], v12
	ds_read_b128 v[4:7], v12 offset:1024
	ds_read_b128 v[8:11], v12 offset:2048
	ds_read_b128 v[12:15], v12 offset:3072
	ds_read_b128 v[16:19], v28
	ds_read_b128 v[20:23], v28 offset:1024
	ds_read_b128 v[24:27], v28 offset:2048
	ds_read_b128 v[28:31], v28 offset:3072
	s_add_u32 s0, s48, 0x80000
	s_addc_u32 s1, s49, 0
	s_mov_b32 m0, s52
	ds_read_b128 v[194:197], v193 offset:32768
	ds_read_b128 v[198:201], v193 offset:33792
	ds_read_b128 v[208:211], v193 offset:34816
	ds_read_b128 v[212:215], v193 offset:35840
	ds_read_b128 v[216:219], v193 offset:36864
	ds_read_b128 v[220:223], v193 offset:37888
	ds_read_b128 v[224:227], v193 offset:38912
	ds_read_b128 v[228:231], v193 offset:39936
	global_load_lds_dwordx4 v160, s[0:1]
	s_mov_b32 m0, s53
	s_nop 0
	global_load_lds_dwordx4 v164, s[0:1]
	s_waitcnt vmcnt(8)
	s_waitcnt lgkmcnt(0)
	s_setprio 3
	s_barrier
	v_mfma_scale_f32_16x16x128_f8f6f4 v[156:159], v[0:7], v[194:201], v[156:159], v186, v186 op_sel_hi:[0,0,0]
	v_mfma_scale_f32_16x16x128_f8f6f4 v[152:155], v[8:15], v[194:201], v[152:155], v186, v186 op_sel_hi:[0,0,0]
	v_mfma_scale_f32_16x16x128_f8f6f4 v[140:143], v[0:7], v[208:215], v[140:143], v186, v186 op_sel_hi:[0,0,0]
	v_mfma_scale_f32_16x16x128_f8f6f4 v[136:139], v[8:15], v[208:215], v[136:139], v186, v186 op_sel_hi:[0,0,0]
	v_mfma_scale_f32_16x16x128_f8f6f4 v[124:127], v[0:7], v[216:223], v[124:127], v186, v186 op_sel_hi:[0,0,0]
	v_mfma_scale_f32_16x16x128_f8f6f4 v[120:123], v[8:15], v[216:223], v[120:123], v186, v186 op_sel_hi:[0,0,0]
	v_mfma_scale_f32_16x16x128_f8f6f4 v[108:111], v[0:7], v[224:231], v[108:111], v186, v186 op_sel_hi:[0,0,0]
	v_mfma_scale_f32_16x16x128_f8f6f4 v[104:107], v[8:15], v[224:231], v[104:107], v186, v186 op_sel_hi:[0,0,0]
	s_setprio 0
	s_setprio 3
	v_mfma_scale_f32_16x16x128_f8f6f4 v[148:151], v[16:23], v[194:201], v[148:151], v186, v186 op_sel_hi:[0,0,0]
	v_mfma_scale_f32_16x16x128_f8f6f4 v[144:147], v[24:31], v[194:201], v[144:147], v186, v186 op_sel_hi:[0,0,0]
	v_mfma_scale_f32_16x16x128_f8f6f4 v[132:135], v[16:23], v[208:215], v[132:135], v186, v186 op_sel_hi:[0,0,0]
	v_mfma_scale_f32_16x16x128_f8f6f4 v[128:131], v[24:31], v[208:215], v[128:131], v186, v186 op_sel_hi:[0,0,0]
	v_mfma_scale_f32_16x16x128_f8f6f4 v[116:119], v[16:23], v[216:223], v[116:119], v186, v186 op_sel_hi:[0,0,0]
	v_mfma_scale_f32_16x16x128_f8f6f4 v[112:115], v[24:31], v[216:223], v[112:115], v186, v186 op_sel_hi:[0,0,0]
	v_mfma_scale_f32_16x16x128_f8f6f4 v[100:103], v[16:23], v[224:231], v[100:103], v186, v186 op_sel_hi:[0,0,0]
	v_mfma_scale_f32_16x16x128_f8f6f4 v[96:99], v[24:31], v[224:231], v[96:99], v186, v186 op_sel_hi:[0,0,0]
	s_barrier
	s_setprio 0
	s_add_i32 s0, s71, s51
	v_lshl_add_u64 v[178:179], v[178:179], 0, s[10:11]
	s_mov_b32 m0, s0
	ds_read_b128 v[194:197], v193 offset:49152
	ds_read_b128 v[198:201], v193 offset:50176
	ds_read_b128 v[208:211], v193 offset:51200
	ds_read_b128 v[212:215], v193 offset:52224
	ds_read_b128 v[216:219], v193 offset:53248
	ds_read_b128 v[220:223], v193 offset:54272
	ds_read_b128 v[224:227], v193 offset:55296
	ds_read_b128 v[228:231], v193 offset:56320
	global_load_lds_dwordx4 v[178:179], off
	s_add_i32 m0, s0, 0x2000
	s_add_u32 s0, s46, 0x80080
	v_lshl_add_u64 v[178:179], v[180:181], 0, s[10:11]
	s_addc_u32 s1, s47, 0
	s_add_i32 s46, s73, s51
	global_load_lds_dwordx4 v[178:179], off
	s_mov_b32 m0, s46
	s_nop 0
	global_load_lds_dwordx4 v162, s[0:1]
	s_add_i32 m0, s46, 0x2000
	s_nop 0
	global_load_lds_dwordx4 v166, s[0:1]
	v_lshl_add_u64 v[178:179], v[182:183], 0, s[10:11]
	s_mov_b32 m0, s55
	s_nop 0
	global_load_lds_dwordx4 v[178:179], off
	v_lshl_add_u64 v[178:179], v[184:185], 0, s[10:11]
	s_mov_b32 m0, s56
	s_nop 0
	global_load_lds_dwordx4 v[178:179], off
	s_waitcnt vmcnt(8)
	s_waitcnt lgkmcnt(0)
	s_setprio 3
	s_barrier
	v_mfma_scale_f32_16x16x128_f8f6f4 v[92:95], v[0:7], v[194:201], v[92:95], v186, v186 op_sel_hi:[0,0,0]
	v_mfma_scale_f32_16x16x128_f8f6f4 v[88:91], v[8:15], v[194:201], v[88:91], v186, v186 op_sel_hi:[0,0,0]
	v_mfma_scale_f32_16x16x128_f8f6f4 v[80:83], v[0:7], v[208:215], v[80:83], v186, v186 op_sel_hi:[0,0,0]
	v_mfma_scale_f32_16x16x128_f8f6f4 v[72:75], v[8:15], v[208:215], v[72:75], v186, v186 op_sel_hi:[0,0,0]
	v_mfma_scale_f32_16x16x128_f8f6f4 v[64:67], v[0:7], v[216:223], v[64:67], v186, v186 op_sel_hi:[0,0,0]
	v_mfma_scale_f32_16x16x128_f8f6f4 v[56:59], v[8:15], v[216:223], v[56:59], v186, v186 op_sel_hi:[0,0,0]
	v_mfma_scale_f32_16x16x128_f8f6f4 v[48:51], v[0:7], v[224:231], v[48:51], v186, v186 op_sel_hi:[0,0,0]
	v_mfma_scale_f32_16x16x128_f8f6f4 v[40:43], v[8:15], v[224:231], v[40:43], v186, v186 op_sel_hi:[0,0,0]
	s_setprio 0
	s_setprio 3
	v_mfma_scale_f32_16x16x128_f8f6f4 v[84:87], v[16:23], v[194:201], v[84:87], v186, v186 op_sel_hi:[0,0,0]
	v_mfma_scale_f32_16x16x128_f8f6f4 v[76:79], v[24:31], v[194:201], v[76:79], v186, v186 op_sel_hi:[0,0,0]
	v_mfma_scale_f32_16x16x128_f8f6f4 v[68:71], v[16:23], v[208:215], v[68:71], v186, v186 op_sel_hi:[0,0,0]
	v_mfma_scale_f32_16x16x128_f8f6f4 v[60:63], v[24:31], v[208:215], v[60:63], v186, v186 op_sel_hi:[0,0,0]
	v_mfma_scale_f32_16x16x128_f8f6f4 v[52:55], v[16:23], v[216:223], v[52:55], v186, v186 op_sel_hi:[0,0,0]
	v_mfma_scale_f32_16x16x128_f8f6f4 v[44:47], v[24:31], v[216:223], v[44:47], v186, v186 op_sel_hi:[0,0,0]
	v_mfma_scale_f32_16x16x128_f8f6f4 v[36:39], v[16:23], v[224:231], v[36:39], v186, v186 op_sel_hi:[0,0,0]
	v_mfma_scale_f32_16x16x128_f8f6f4 v[32:35], v[24:31], v[224:231], v[32:35], v186, v186 op_sel_hi:[0,0,0]
	s_barrier
	s_setprio 0
	s_add_u32 s44, s44, 0x100
	s_addc_u32 s45, s45, 0
	s_add_i32 s70, s70, 2
	s_add_u32 s68, s68, 0x100
	s_addc_u32 s69, s69, 0
	s_cmp_gt_u32 s70, 29
	s_cbranch_scc0 .LBB0_705
	s_and_b64 vcc, exec, s[12:13]
	s_cbranch_vccz .LBB0_708
	s_barrier

.LBB0_1637:
	ds_read_b128 v[152:155], v149
	ds_read_b128 v[156:159], v149 offset:1024
	ds_read_b128 v[160:163], v149 offset:2048
	ds_read_b128 v[164:167], v149 offset:3072
	ds_read_b128 v[168:171], v150
	ds_read_b128 v[172:175], v150 offset:1024
	ds_read_b128 v[176:179], v150 offset:2048
	ds_read_b128 v[180:183], v150 offset:3072
	s_add_u32 s0, s42, 0xfff00080
	s_addc_u32 s1, s43, -1
	s_cmp_eq_u32 s68, 60
	s_cselect_b32 s47, s35, s1
	s_cselect_b32 s46, s64, s0
	s_cselect_b32 s45, s31, s67
	s_cselect_b32 s44, s65, s66
	s_add_i32 m0, s41, 0xc000
	ds_read_b128 v[184:187], v151
	ds_read_b128 v[188:191], v151 offset:1024
	ds_read_b128 v[192:195], v151 offset:2048
	ds_read_b128 v[196:199], v151 offset:3072
	ds_read_b128 v[200:203], v151 offset:4096
	ds_read_b128 v[210:213], v151 offset:5120
	ds_read_b128 v[214:217], v151 offset:6144
	ds_read_b128 v[218:221], v151 offset:7168
	global_load_lds_dwordx4 v136, s[42:43]
	s_add_i32 m0, s41, 0xe000
	s_nop 0
	global_load_lds_dwordx4 v138, s[42:43]
	s_waitcnt vmcnt(8)
	s_waitcnt lgkmcnt(0)
	s_setprio 3
	s_barrier
	v_mfma_f32_16x16x32_bf16 v[124:127], v[152:155], v[184:187], v[124:127]
	v_mfma_f32_16x16x32_bf16 v[120:123], v[160:163], v[184:187], v[120:123]
	v_mfma_f32_16x16x32_bf16 v[116:119], v[152:155], v[192:195], v[116:119]
	v_mfma_f32_16x16x32_bf16 v[108:111], v[160:163], v[192:195], v[108:111]
	v_mfma_f32_16x16x32_bf16 v[100:103], v[152:155], v[200:203], v[100:103]
	v_mfma_f32_16x16x32_bf16 v[92:95], v[160:163], v[200:203], v[92:95]
	v_mfma_f32_16x16x32_bf16 v[84:87], v[152:155], v[214:217], v[84:87]
	v_mfma_f32_16x16x32_bf16 v[76:79], v[160:163], v[214:217], v[76:79]
	v_mfma_f32_16x16x32_bf16 v[124:127], v[156:159], v[188:191], v[124:127]
	v_mfma_f32_16x16x32_bf16 v[120:123], v[164:167], v[188:191], v[120:123]
	v_mfma_f32_16x16x32_bf16 v[116:119], v[156:159], v[196:199], v[116:119]
	v_mfma_f32_16x16x32_bf16 v[108:111], v[164:167], v[196:199], v[108:111]
	v_mfma_f32_16x16x32_bf16 v[100:103], v[156:159], v[210:213], v[100:103]
	v_mfma_f32_16x16x32_bf16 v[92:95], v[164:167], v[210:213], v[92:95]
	v_mfma_f32_16x16x32_bf16 v[84:87], v[156:159], v[218:221], v[84:87]
	v_mfma_f32_16x16x32_bf16 v[76:79], v[164:167], v[218:221], v[76:79]
	s_setprio 0
	s_setprio 3
	v_mfma_f32_16x16x32_bf16 v[112:115], v[168:171], v[184:187], v[112:115]
	v_mfma_f32_16x16x32_bf16 v[104:107], v[176:179], v[184:187], v[104:107]
	v_mfma_f32_16x16x32_bf16 v[96:99], v[168:171], v[192:195], v[96:99]
	v_mfma_f32_16x16x32_bf16 v[88:91], v[176:179], v[192:195], v[88:91]
	v_mfma_f32_16x16x32_bf16 v[80:83], v[168:171], v[200:203], v[80:83]
	v_mfma_f32_16x16x32_bf16 v[72:75], v[176:179], v[200:203], v[72:75]
	v_mfma_f32_16x16x32_bf16 v[68:71], v[168:171], v[214:217], v[68:71]
	v_mfma_f32_16x16x32_bf16 v[64:67], v[176:179], v[214:217], v[64:67]
	v_mfma_f32_16x16x32_bf16 v[112:115], v[172:175], v[188:191], v[112:115]
	v_mfma_f32_16x16x32_bf16 v[104:107], v[180:183], v[188:191], v[104:107]
	v_mfma_f32_16x16x32_bf16 v[96:99], v[172:175], v[196:199], v[96:99]
	v_mfma_f32_16x16x32_bf16 v[88:91], v[180:183], v[196:199], v[88:91]
	v_mfma_f32_16x16x32_bf16 v[80:83], v[172:175], v[210:213], v[80:83]
	v_mfma_f32_16x16x32_bf16 v[72:75], v[180:183], v[210:213], v[72:75]
	v_mfma_f32_16x16x32_bf16 v[68:71], v[172:175], v[218:221], v[68:71]
	v_mfma_f32_16x16x32_bf16 v[64:67], v[180:183], v[218:221], v[64:67]
	s_barrier
	s_setprio 0
	s_add_i32 s0, s57, s49
	v_lshl_add_u64 v[144:145], s[44:45], 0, v[130:131]
	s_mov_b32 m0, s0
	ds_read_b128 v[184:187], v151 offset:16384
	ds_read_b128 v[188:191], v151 offset:17408
	ds_read_b128 v[192:195], v151 offset:18432
	ds_read_b128 v[196:199], v151 offset:19456
	ds_read_b128 v[200:203], v151 offset:20480
	ds_read_b128 v[210:213], v151 offset:21504
	ds_read_b128 v[214:217], v151 offset:22528
	ds_read_b128 v[218:221], v151 offset:23552
	global_load_lds_dwordx4 v[144:145], off
	s_add_i32 m0, s0, 0x2000
	s_add_u32 s0, s44, 0x100000
	v_lshl_add_u64 v[222:223], s[44:45], 0, v[134:135]
	s_addc_u32 s1, s45, 0
	s_add_i32 s69, s58, s49
	global_load_lds_dwordx4 v[222:223], off
	s_mov_b32 m0, s69
	v_lshl_add_u64 v[226:227], s[46:47], 0, v[132:133]
	global_load_lds_dwordx4 v130, s[0:1]
	s_add_i32 m0, s69, 0x2000
	s_nop 0
	global_load_lds_dwordx4 v134, s[0:1]
	v_lshl_add_u64 v[224:225], s[46:47], 0, v[128:129]
	s_mov_b32 m0, s41
	s_nop 0
	global_load_lds_dwordx4 v[224:225], off
	s_mov_b32 m0, s50
	s_nop 0
	global_load_lds_dwordx4 v[226:227], off
	s_waitcnt vmcnt(8)
	s_waitcnt lgkmcnt(0)
	s_setprio 3
	s_barrier
	v_mfma_f32_16x16x32_bf16 v[60:63], v[152:155], v[184:187], v[60:63]
	v_mfma_f32_16x16x32_bf16 v[56:59], v[160:163], v[184:187], v[56:59]
	v_mfma_f32_16x16x32_bf16 v[52:55], v[152:155], v[192:195], v[52:55]
	v_mfma_f32_16x16x32_bf16 v[44:47], v[160:163], v[192:195], v[44:47]
	v_mfma_f32_16x16x32_bf16 v[36:39], v[152:155], v[200:203], v[36:39]
	v_mfma_f32_16x16x32_bf16 v[28:31], v[160:163], v[200:203], v[28:31]
	v_mfma_f32_16x16x32_bf16 v[20:23], v[152:155], v[214:217], v[20:23]
	v_mfma_f32_16x16x32_bf16 v[12:15], v[160:163], v[214:217], v[12:15]
	v_mfma_f32_16x16x32_bf16 v[60:63], v[156:159], v[188:191], v[60:63]
	v_mfma_f32_16x16x32_bf16 v[56:59], v[164:167], v[188:191], v[56:59]
	v_mfma_f32_16x16x32_bf16 v[52:55], v[156:159], v[196:199], v[52:55]
	v_mfma_f32_16x16x32_bf16 v[44:47], v[164:167], v[196:199], v[44:47]
	v_mfma_f32_16x16x32_bf16 v[36:39], v[156:159], v[210:213], v[36:39]
	v_mfma_f32_16x16x32_bf16 v[28:31], v[164:167], v[210:213], v[28:31]
	v_mfma_f32_16x16x32_bf16 v[20:23], v[156:159], v[218:221], v[20:23]
	v_mfma_f32_16x16x32_bf16 v[12:15], v[164:167], v[218:221], v[12:15]
	s_setprio 0
	s_setprio 3
	v_mfma_f32_16x16x32_bf16 v[48:51], v[168:171], v[184:187], v[48:51]
	v_mfma_f32_16x16x32_bf16 v[40:43], v[176:179], v[184:187], v[40:43]
	v_mfma_f32_16x16x32_bf16 v[32:35], v[168:171], v[192:195], v[32:35]
	v_mfma_f32_16x16x32_bf16 v[24:27], v[176:179], v[192:195], v[24:27]
	v_mfma_f32_16x16x32_bf16 v[16:19], v[168:171], v[200:203], v[16:19]
	v_mfma_f32_16x16x32_bf16 v[8:11], v[176:179], v[200:203], v[8:11]
	v_mfma_f32_16x16x32_bf16 v[4:7], v[168:171], v[214:217], v[4:7]
	v_mfma_f32_16x16x32_bf16 v[0:3], v[176:179], v[214:217], v[0:3]
	v_mfma_f32_16x16x32_bf16 v[48:51], v[172:175], v[188:191], v[48:51]
	v_mfma_f32_16x16x32_bf16 v[40:43], v[180:183], v[188:191], v[40:43]
	v_mfma_f32_16x16x32_bf16 v[32:35], v[172:175], v[196:199], v[32:35]
	v_mfma_f32_16x16x32_bf16 v[24:27], v[180:183], v[196:199], v[24:27]
	v_mfma_f32_16x16x32_bf16 v[16:19], v[172:175], v[210:213], v[16:19]
	v_mfma_f32_16x16x32_bf16 v[8:11], v[180:183], v[210:213], v[8:11]
	v_mfma_f32_16x16x32_bf16 v[4:7], v[172:175], v[218:221], v[4:7]
	v_mfma_f32_16x16x32_bf16 v[0:3], v[180:183], v[218:221], v[0:3]
	s_barrier
	s_setprio 0
	s_add_i32 s69, 0, 0x18000
	s_add_i32 s70, 0, 0x1c000
	v_add_u32_e32 v164, s69, v147
	v_add_u32_e32 v180, s70, v147
	ds_read_b128 v[152:155], v164
	ds_read_b128 v[156:159], v164 offset:1024
	ds_read_b128 v[160:163], v164 offset:2048
	ds_read_b128 v[164:167], v164 offset:3072
	ds_read_b128 v[168:171], v180
	ds_read_b128 v[172:175], v180 offset:1024
	ds_read_b128 v[176:179], v180 offset:2048
	ds_read_b128 v[180:183], v180 offset:3072
	s_add_u32 s0, s46, 0x100000
	s_addc_u32 s1, s47, 0
	s_mov_b32 m0, s51
	ds_read_b128 v[184:187], v151 offset:32768
	ds_read_b128 v[188:191], v151 offset:33792
	ds_read_b128 v[192:195], v151 offset:34816
	ds_read_b128 v[196:199], v151 offset:35840
	ds_read_b128 v[200:203], v151 offset:36864
	ds_read_b128 v[210:213], v151 offset:37888
	ds_read_b128 v[214:217], v151 offset:38912
	ds_read_b128 v[218:221], v151 offset:39936
	global_load_lds_dwordx4 v128, s[0:1]
	s_mov_b32 m0, s52
	s_nop 0
	global_load_lds_dwordx4 v132, s[0:1]
	s_waitcnt vmcnt(8)
	s_waitcnt lgkmcnt(0)
	s_setprio 3
	s_barrier
	v_mfma_f32_16x16x32_bf16 v[124:127], v[152:155], v[184:187], v[124:127]
	v_mfma_f32_16x16x32_bf16 v[120:123], v[160:163], v[184:187], v[120:123]
	v_mfma_f32_16x16x32_bf16 v[116:119], v[152:155], v[192:195], v[116:119]
	v_mfma_f32_16x16x32_bf16 v[108:111], v[160:163], v[192:195], v[108:111]
	v_mfma_f32_16x16x32_bf16 v[100:103], v[152:155], v[200:203], v[100:103]
	v_mfma_f32_16x16x32_bf16 v[92:95], v[160:163], v[200:203], v[92:95]
	v_mfma_f32_16x16x32_bf16 v[84:87], v[152:155], v[214:217], v[84:87]
	v_mfma_f32_16x16x32_bf16 v[76:79], v[160:163], v[214:217], v[76:79]
	v_mfma_f32_16x16x32_bf16 v[124:127], v[156:159], v[188:191], v[124:127]
	v_mfma_f32_16x16x32_bf16 v[120:123], v[164:167], v[188:191], v[120:123]
	v_mfma_f32_16x16x32_bf16 v[116:119], v[156:159], v[196:199], v[116:119]
	v_mfma_f32_16x16x32_bf16 v[108:111], v[164:167], v[196:199], v[108:111]
	v_mfma_f32_16x16x32_bf16 v[100:103], v[156:159], v[210:213], v[100:103]
	v_mfma_f32_16x16x32_bf16 v[92:95], v[164:167], v[210:213], v[92:95]
	v_mfma_f32_16x16x32_bf16 v[84:87], v[156:159], v[218:221], v[84:87]
	v_mfma_f32_16x16x32_bf16 v[76:79], v[164:167], v[218:221], v[76:79]
	s_setprio 0
	s_setprio 3
	v_mfma_f32_16x16x32_bf16 v[112:115], v[168:171], v[184:187], v[112:115]
	v_mfma_f32_16x16x32_bf16 v[104:107], v[176:179], v[184:187], v[104:107]
	v_mfma_f32_16x16x32_bf16 v[96:99], v[168:171], v[192:195], v[96:99]
	v_mfma_f32_16x16x32_bf16 v[88:91], v[176:179], v[192:195], v[88:91]
	v_mfma_f32_16x16x32_bf16 v[80:83], v[168:171], v[200:203], v[80:83]
	v_mfma_f32_16x16x32_bf16 v[72:75], v[176:179], v[200:203], v[72:75]
	v_mfma_f32_16x16x32_bf16 v[68:71], v[168:171], v[214:217], v[68:71]
	v_mfma_f32_16x16x32_bf16 v[64:67], v[176:179], v[214:217], v[64:67]
	v_mfma_f32_16x16x32_bf16 v[112:115], v[172:175], v[188:191], v[112:115]
	v_mfma_f32_16x16x32_bf16 v[104:107], v[180:183], v[188:191], v[104:107]
	v_mfma_f32_16x16x32_bf16 v[96:99], v[172:175], v[196:199], v[96:99]
	v_mfma_f32_16x16x32_bf16 v[88:91], v[180:183], v[196:199], v[88:91]
	v_mfma_f32_16x16x32_bf16 v[80:83], v[172:175], v[210:213], v[80:83]
	v_mfma_f32_16x16x32_bf16 v[72:75], v[180:183], v[210:213], v[72:75]
	v_mfma_f32_16x16x32_bf16 v[68:71], v[172:175], v[218:221], v[68:71]
	v_mfma_f32_16x16x32_bf16 v[64:67], v[180:183], v[218:221], v[64:67]
	s_barrier
	s_setprio 0
	s_add_i32 s0, s69, s49
	v_lshl_add_u64 v[144:145], v[144:145], 0, s[14:15]
	s_mov_b32 m0, s0
	ds_read_b128 v[184:187], v151 offset:49152
	ds_read_b128 v[188:191], v151 offset:50176
	ds_read_b128 v[192:195], v151 offset:51200
	ds_read_b128 v[196:199], v151 offset:52224
	ds_read_b128 v[200:203], v151 offset:53248
	ds_read_b128 v[210:213], v151 offset:54272
	ds_read_b128 v[214:217], v151 offset:55296
	ds_read_b128 v[218:221], v151 offset:56320
	global_load_lds_dwordx4 v[144:145], off
	s_add_i32 m0, s0, 0x2000
	s_add_u32 s0, s44, 0x100080
	v_lshl_add_u64 v[144:145], v[222:223], 0, s[14:15]
	s_addc_u32 s1, s45, 0
	s_add_i32 s44, s70, s49
	global_load_lds_dwordx4 v[144:145], off
	s_mov_b32 m0, s44
	s_nop 0
	global_load_lds_dwordx4 v130, s[0:1]
	s_add_i32 m0, s44, 0x2000
	s_nop 0
	global_load_lds_dwordx4 v134, s[0:1]
	v_lshl_add_u64 v[144:145], v[224:225], 0, s[14:15]
	s_mov_b32 m0, s54
	s_nop 0
	global_load_lds_dwordx4 v[144:145], off
	v_lshl_add_u64 v[144:145], v[226:227], 0, s[14:15]
	s_mov_b32 m0, s55
	s_nop 0
	global_load_lds_dwordx4 v[144:145], off
	s_waitcnt vmcnt(8)
	s_waitcnt lgkmcnt(0)
	s_setprio 3
	s_barrier
	v_mfma_f32_16x16x32_bf16 v[60:63], v[152:155], v[184:187], v[60:63]
	v_mfma_f32_16x16x32_bf16 v[56:59], v[160:163], v[184:187], v[56:59]
	v_mfma_f32_16x16x32_bf16 v[52:55], v[152:155], v[192:195], v[52:55]
	v_mfma_f32_16x16x32_bf16 v[44:47], v[160:163], v[192:195], v[44:47]
	v_mfma_f32_16x16x32_bf16 v[36:39], v[152:155], v[200:203], v[36:39]
	v_mfma_f32_16x16x32_bf16 v[28:31], v[160:163], v[200:203], v[28:31]
	v_mfma_f32_16x16x32_bf16 v[20:23], v[152:155], v[214:217], v[20:23]
	v_mfma_f32_16x16x32_bf16 v[12:15], v[160:163], v[214:217], v[12:15]
	v_mfma_f32_16x16x32_bf16 v[60:63], v[156:159], v[188:191], v[60:63]
	v_mfma_f32_16x16x32_bf16 v[56:59], v[164:167], v[188:191], v[56:59]
	v_mfma_f32_16x16x32_bf16 v[52:55], v[156:159], v[196:199], v[52:55]
	v_mfma_f32_16x16x32_bf16 v[44:47], v[164:167], v[196:199], v[44:47]
	v_mfma_f32_16x16x32_bf16 v[36:39], v[156:159], v[210:213], v[36:39]
	v_mfma_f32_16x16x32_bf16 v[28:31], v[164:167], v[210:213], v[28:31]
	v_mfma_f32_16x16x32_bf16 v[20:23], v[156:159], v[218:221], v[20:23]
	v_mfma_f32_16x16x32_bf16 v[12:15], v[164:167], v[218:221], v[12:15]
	s_setprio 0
	s_setprio 3
	v_mfma_f32_16x16x32_bf16 v[48:51], v[168:171], v[184:187], v[48:51]
	v_mfma_f32_16x16x32_bf16 v[40:43], v[176:179], v[184:187], v[40:43]
	v_mfma_f32_16x16x32_bf16 v[32:35], v[168:171], v[192:195], v[32:35]
	v_mfma_f32_16x16x32_bf16 v[24:27], v[176:179], v[192:195], v[24:27]
	v_mfma_f32_16x16x32_bf16 v[16:19], v[168:171], v[200:203], v[16:19]
	v_mfma_f32_16x16x32_bf16 v[8:11], v[176:179], v[200:203], v[8:11]
	v_mfma_f32_16x16x32_bf16 v[4:7], v[168:171], v[214:217], v[4:7]
	v_mfma_f32_16x16x32_bf16 v[0:3], v[176:179], v[214:217], v[0:3]
	v_mfma_f32_16x16x32_bf16 v[48:51], v[172:175], v[188:191], v[48:51]
	v_mfma_f32_16x16x32_bf16 v[40:43], v[180:183], v[188:191], v[40:43]
	v_mfma_f32_16x16x32_bf16 v[32:35], v[172:175], v[196:199], v[32:35]
	v_mfma_f32_16x16x32_bf16 v[24:27], v[180:183], v[196:199], v[24:27]
	v_mfma_f32_16x16x32_bf16 v[16:19], v[172:175], v[210:213], v[16:19]
	v_mfma_f32_16x16x32_bf16 v[8:11], v[180:183], v[210:213], v[8:11]
	v_mfma_f32_16x16x32_bf16 v[4:7], v[172:175], v[218:221], v[4:7]
	v_mfma_f32_16x16x32_bf16 v[0:3], v[180:183], v[218:221], v[0:3]
	s_barrier
	s_setprio 0
	s_add_u32 s42, s42, 0x100
	s_addc_u32 s43, s43, 0
	s_add_i32 s68, s68, 2
	s_add_u32 s66, s66, 0x100
	s_addc_u32 s67, s67, 0
	s_cmp_gt_u32 s68, 61
	s_cbranch_scc0 .LBB0_1637
	s_and_b64 vcc, exec, s[16:17]
	s_cbranch_vccz .LBB0_1640
	s_barrier

.LBB0_1813:
	ds_read_b128 v[148:151], v156
	ds_read_b128 v[160:163], v156 offset:1024
	ds_read_b128 v[164:167], v156 offset:2048
	ds_read_b128 v[168:171], v156 offset:3072
	ds_read_b128 v[172:175], v157
	ds_read_b128 v[176:179], v157 offset:1024
	ds_read_b128 v[180:183], v157 offset:2048
	ds_read_b128 v[184:187], v157 offset:3072
	s_add_u32 s0, s36, 0xfff00080
	s_addc_u32 s1, s37, -1
	s_cmp_eq_u32 s64, 60
	s_cselect_b32 s41, s59, s1
	s_cselect_b32 s40, s60, s0
	s_cselect_b32 s39, s17, s63
	s_cselect_b32 s38, s61, s62
	s_add_i32 m0, s31, 0xc000
	ds_read_b128 v[188:191], v158
	ds_read_b128 v[192:195], v158 offset:1024
	ds_read_b128 v[196:199], v158 offset:2048
	ds_read_b128 v[200:203], v158 offset:3072
	ds_read_b128 v[210:213], v158 offset:4096
	ds_read_b128 v[214:217], v158 offset:5120
	ds_read_b128 v[218:221], v158 offset:6144
	ds_read_b128 v[222:225], v158 offset:7168
	global_load_lds_dwordx4 v140, s[36:37]
	s_add_i32 m0, s31, 0xe000
	s_nop 0
	global_load_lds_dwordx4 v142, s[36:37]
	s_waitcnt vmcnt(8)
	s_waitcnt lgkmcnt(0)
	s_setprio 3
	s_barrier
	v_mfma_f32_16x16x32_bf16 v[124:127], v[148:151], v[188:191], v[124:127]
	v_mfma_f32_16x16x32_bf16 v[120:123], v[164:167], v[188:191], v[120:123]
	v_mfma_f32_16x16x32_bf16 v[108:111], v[148:151], v[196:199], v[108:111]
	v_mfma_f32_16x16x32_bf16 v[104:107], v[164:167], v[196:199], v[104:107]
	v_mfma_f32_16x16x32_bf16 v[92:95], v[148:151], v[210:213], v[92:95]
	v_mfma_f32_16x16x32_bf16 v[88:91], v[164:167], v[210:213], v[88:91]
	v_mfma_f32_16x16x32_bf16 v[76:79], v[148:151], v[218:221], v[76:79]
	v_mfma_f32_16x16x32_bf16 v[72:75], v[164:167], v[218:221], v[72:75]
	v_mfma_f32_16x16x32_bf16 v[124:127], v[160:163], v[192:195], v[124:127]
	v_mfma_f32_16x16x32_bf16 v[120:123], v[168:171], v[192:195], v[120:123]
	v_mfma_f32_16x16x32_bf16 v[108:111], v[160:163], v[200:203], v[108:111]
	v_mfma_f32_16x16x32_bf16 v[104:107], v[168:171], v[200:203], v[104:107]
	v_mfma_f32_16x16x32_bf16 v[92:95], v[160:163], v[214:217], v[92:95]
	v_mfma_f32_16x16x32_bf16 v[88:91], v[168:171], v[214:217], v[88:91]
	v_mfma_f32_16x16x32_bf16 v[76:79], v[160:163], v[222:225], v[76:79]
	v_mfma_f32_16x16x32_bf16 v[72:75], v[168:171], v[222:225], v[72:75]
	s_setprio 0
	s_setprio 3
	v_mfma_f32_16x16x32_bf16 v[116:119], v[172:175], v[188:191], v[116:119]
	v_mfma_f32_16x16x32_bf16 v[112:115], v[180:183], v[188:191], v[112:115]
	v_mfma_f32_16x16x32_bf16 v[100:103], v[172:175], v[196:199], v[100:103]
	v_mfma_f32_16x16x32_bf16 v[96:99], v[180:183], v[196:199], v[96:99]
	v_mfma_f32_16x16x32_bf16 v[84:87], v[172:175], v[210:213], v[84:87]
	v_mfma_f32_16x16x32_bf16 v[80:83], v[180:183], v[210:213], v[80:83]
	v_mfma_f32_16x16x32_bf16 v[68:71], v[172:175], v[218:221], v[68:71]
	v_mfma_f32_16x16x32_bf16 v[64:67], v[180:183], v[218:221], v[64:67]
	v_mfma_f32_16x16x32_bf16 v[116:119], v[176:179], v[192:195], v[116:119]
	v_mfma_f32_16x16x32_bf16 v[112:115], v[184:187], v[192:195], v[112:115]
	v_mfma_f32_16x16x32_bf16 v[100:103], v[176:179], v[200:203], v[100:103]
	v_mfma_f32_16x16x32_bf16 v[96:99], v[184:187], v[200:203], v[96:99]
	v_mfma_f32_16x16x32_bf16 v[84:87], v[176:179], v[214:217], v[84:87]
	v_mfma_f32_16x16x32_bf16 v[80:83], v[184:187], v[214:217], v[80:83]
	v_mfma_f32_16x16x32_bf16 v[68:71], v[176:179], v[222:225], v[68:71]
	v_mfma_f32_16x16x32_bf16 v[64:67], v[184:187], v[222:225], v[64:67]
	s_barrier
	s_setprio 0
	s_add_i32 s0, s52, s43
	v_lshl_add_u64 v[226:227], s[38:39], 0, v[132:133]
	s_mov_b32 m0, s0
	ds_read_b128 v[188:191], v158 offset:16384
	ds_read_b128 v[192:195], v158 offset:17408
	ds_read_b128 v[196:199], v158 offset:18432
	ds_read_b128 v[200:203], v158 offset:19456
	ds_read_b128 v[210:213], v158 offset:20480
	ds_read_b128 v[214:217], v158 offset:21504
	ds_read_b128 v[218:221], v158 offset:22528
	ds_read_b128 v[222:225], v158 offset:23552
	global_load_lds_dwordx4 v[226:227], off
	s_add_i32 m0, s0, 0x2000
	s_add_u32 s0, s38, 0x100000
	v_lshl_add_u64 v[228:229], s[38:39], 0, v[136:137]
	s_addc_u32 s1, s39, 0
	s_add_i32 s65, s53, s43
	global_load_lds_dwordx4 v[228:229], off
	s_mov_b32 m0, s65
	v_lshl_add_u64 v[232:233], s[40:41], 0, v[134:135]
	global_load_lds_dwordx4 v132, s[0:1]
	s_add_i32 m0, s65, 0x2000
	s_nop 0
	global_load_lds_dwordx4 v136, s[0:1]
	v_lshl_add_u64 v[230:231], s[40:41], 0, v[130:131]
	s_mov_b32 m0, s31
	s_nop 0
	global_load_lds_dwordx4 v[230:231], off
	s_mov_b32 m0, s35
	s_nop 0
	global_load_lds_dwordx4 v[232:233], off
	s_waitcnt vmcnt(8)
	s_waitcnt lgkmcnt(0)
	s_setprio 3
	s_barrier
	v_mfma_f32_16x16x32_bf16 v[60:63], v[148:151], v[188:191], v[60:63]
	v_mfma_f32_16x16x32_bf16 v[56:59], v[164:167], v[188:191], v[56:59]
	v_mfma_f32_16x16x32_bf16 v[44:47], v[148:151], v[196:199], v[44:47]
	v_mfma_f32_16x16x32_bf16 v[40:43], v[164:167], v[196:199], v[40:43]
	v_mfma_f32_16x16x32_bf16 v[28:31], v[148:151], v[210:213], v[28:31]
	v_mfma_f32_16x16x32_bf16 v[24:27], v[164:167], v[210:213], v[24:27]
	v_mfma_f32_16x16x32_bf16 v[12:15], v[148:151], v[218:221], v[12:15]
	v_mfma_f32_16x16x32_bf16 v[8:11], v[164:167], v[218:221], v[8:11]
	v_mfma_f32_16x16x32_bf16 v[60:63], v[160:163], v[192:195], v[60:63]
	v_mfma_f32_16x16x32_bf16 v[56:59], v[168:171], v[192:195], v[56:59]
	v_mfma_f32_16x16x32_bf16 v[44:47], v[160:163], v[200:203], v[44:47]
	v_mfma_f32_16x16x32_bf16 v[40:43], v[168:171], v[200:203], v[40:43]
	v_mfma_f32_16x16x32_bf16 v[28:31], v[160:163], v[214:217], v[28:31]
	v_mfma_f32_16x16x32_bf16 v[24:27], v[168:171], v[214:217], v[24:27]
	v_mfma_f32_16x16x32_bf16 v[12:15], v[160:163], v[222:225], v[12:15]
	v_mfma_f32_16x16x32_bf16 v[8:11], v[168:171], v[222:225], v[8:11]
	s_setprio 0
	s_setprio 3
	v_mfma_f32_16x16x32_bf16 v[52:55], v[172:175], v[188:191], v[52:55]
	v_mfma_f32_16x16x32_bf16 v[48:51], v[180:183], v[188:191], v[48:51]
	v_mfma_f32_16x16x32_bf16 v[36:39], v[172:175], v[196:199], v[36:39]
	v_mfma_f32_16x16x32_bf16 v[32:35], v[180:183], v[196:199], v[32:35]
	v_mfma_f32_16x16x32_bf16 v[20:23], v[172:175], v[210:213], v[20:23]
	v_mfma_f32_16x16x32_bf16 v[16:19], v[180:183], v[210:213], v[16:19]
	v_mfma_f32_16x16x32_bf16 v[4:7], v[172:175], v[218:221], v[4:7]
	v_mfma_f32_16x16x32_bf16 v[0:3], v[180:183], v[218:221], v[0:3]
	v_mfma_f32_16x16x32_bf16 v[52:55], v[176:179], v[192:195], v[52:55]
	v_mfma_f32_16x16x32_bf16 v[48:51], v[184:187], v[192:195], v[48:51]
	v_mfma_f32_16x16x32_bf16 v[36:39], v[176:179], v[200:203], v[36:39]
	v_mfma_f32_16x16x32_bf16 v[32:35], v[184:187], v[200:203], v[32:35]
	v_mfma_f32_16x16x32_bf16 v[20:23], v[176:179], v[214:217], v[20:23]
	v_mfma_f32_16x16x32_bf16 v[16:19], v[184:187], v[214:217], v[16:19]
	v_mfma_f32_16x16x32_bf16 v[4:7], v[176:179], v[222:225], v[4:7]
	v_mfma_f32_16x16x32_bf16 v[0:3], v[184:187], v[222:225], v[0:3]
	s_barrier
	s_setprio 0
	s_add_i32 s65, 0, 0x18000
	v_add_u32_e32 v128, s65, v153
	s_add_i32 s66, 0, 0x1c000
	ds_read_b128 v[148:151], v128
	ds_read_b128 v[160:163], v128 offset:1024
	ds_read_b128 v[164:167], v128 offset:2048
	ds_read_b128 v[168:171], v128 offset:3072
	v_add_u32_e32 v128, s66, v153
	ds_read_b128 v[172:175], v128
	ds_read_b128 v[176:179], v128 offset:1024
	ds_read_b128 v[180:183], v128 offset:2048
	ds_read_b128 v[184:187], v128 offset:3072
	s_add_u32 s0, s40, 0x100000
	s_addc_u32 s1, s41, 0
	s_mov_b32 m0, s44
	ds_read_b128 v[188:191], v158 offset:32768
	ds_read_b128 v[192:195], v158 offset:33792
	ds_read_b128 v[196:199], v158 offset:34816
	ds_read_b128 v[200:203], v158 offset:35840
	ds_read_b128 v[210:213], v158 offset:36864
	ds_read_b128 v[214:217], v158 offset:37888
	ds_read_b128 v[218:221], v158 offset:38912
	ds_read_b128 v[222:225], v158 offset:39936
	global_load_lds_dwordx4 v130, s[0:1]
	s_mov_b32 m0, s45
	s_nop 0
	global_load_lds_dwordx4 v134, s[0:1]
	s_waitcnt vmcnt(8)
	s_waitcnt lgkmcnt(0)
	s_setprio 3
	s_barrier
	v_mfma_f32_16x16x32_bf16 v[124:127], v[148:151], v[188:191], v[124:127]
	v_mfma_f32_16x16x32_bf16 v[120:123], v[164:167], v[188:191], v[120:123]
	v_mfma_f32_16x16x32_bf16 v[108:111], v[148:151], v[196:199], v[108:111]
	v_mfma_f32_16x16x32_bf16 v[104:107], v[164:167], v[196:199], v[104:107]
	v_mfma_f32_16x16x32_bf16 v[92:95], v[148:151], v[210:213], v[92:95]
	v_mfma_f32_16x16x32_bf16 v[88:91], v[164:167], v[210:213], v[88:91]
	v_mfma_f32_16x16x32_bf16 v[76:79], v[148:151], v[218:221], v[76:79]
	v_mfma_f32_16x16x32_bf16 v[72:75], v[164:167], v[218:221], v[72:75]
	v_mfma_f32_16x16x32_bf16 v[124:127], v[160:163], v[192:195], v[124:127]
	v_mfma_f32_16x16x32_bf16 v[120:123], v[168:171], v[192:195], v[120:123]
	v_mfma_f32_16x16x32_bf16 v[108:111], v[160:163], v[200:203], v[108:111]
	v_mfma_f32_16x16x32_bf16 v[104:107], v[168:171], v[200:203], v[104:107]
	v_mfma_f32_16x16x32_bf16 v[92:95], v[160:163], v[214:217], v[92:95]
	v_mfma_f32_16x16x32_bf16 v[88:91], v[168:171], v[214:217], v[88:91]
	v_mfma_f32_16x16x32_bf16 v[76:79], v[160:163], v[222:225], v[76:79]
	v_mfma_f32_16x16x32_bf16 v[72:75], v[168:171], v[222:225], v[72:75]
	s_setprio 0
	s_setprio 3
	v_mfma_f32_16x16x32_bf16 v[116:119], v[172:175], v[188:191], v[116:119]
	v_mfma_f32_16x16x32_bf16 v[112:115], v[180:183], v[188:191], v[112:115]
	v_mfma_f32_16x16x32_bf16 v[100:103], v[172:175], v[196:199], v[100:103]
	v_mfma_f32_16x16x32_bf16 v[96:99], v[180:183], v[196:199], v[96:99]
	v_mfma_f32_16x16x32_bf16 v[84:87], v[172:175], v[210:213], v[84:87]
	v_mfma_f32_16x16x32_bf16 v[80:83], v[180:183], v[210:213], v[80:83]
	v_mfma_f32_16x16x32_bf16 v[68:71], v[172:175], v[218:221], v[68:71]
	v_mfma_f32_16x16x32_bf16 v[64:67], v[180:183], v[218:221], v[64:67]
	v_mfma_f32_16x16x32_bf16 v[116:119], v[176:179], v[192:195], v[116:119]
	v_mfma_f32_16x16x32_bf16 v[112:115], v[184:187], v[192:195], v[112:115]
	v_mfma_f32_16x16x32_bf16 v[100:103], v[176:179], v[200:203], v[100:103]
	v_mfma_f32_16x16x32_bf16 v[96:99], v[184:187], v[200:203], v[96:99]
	v_mfma_f32_16x16x32_bf16 v[84:87], v[176:179], v[214:217], v[84:87]
	v_mfma_f32_16x16x32_bf16 v[80:83], v[184:187], v[214:217], v[80:83]
	v_mfma_f32_16x16x32_bf16 v[68:71], v[176:179], v[222:225], v[68:71]
	v_mfma_f32_16x16x32_bf16 v[64:67], v[184:187], v[222:225], v[64:67]
	s_barrier
	s_setprio 0
	s_add_i32 s0, s65, s43
	v_lshl_add_u64 v[226:227], v[226:227], 0, s[12:13]
	s_mov_b32 m0, s0
	ds_read_b128 v[188:191], v158 offset:49152
	ds_read_b128 v[192:195], v158 offset:50176
	ds_read_b128 v[196:199], v158 offset:51200
	ds_read_b128 v[200:203], v158 offset:52224
	ds_read_b128 v[210:213], v158 offset:53248
	ds_read_b128 v[214:217], v158 offset:54272
	ds_read_b128 v[218:221], v158 offset:55296
	ds_read_b128 v[222:225], v158 offset:56320
	global_load_lds_dwordx4 v[226:227], off
	s_add_i32 m0, s0, 0x2000
	s_add_u32 s0, s38, 0x100080
	v_lshl_add_u64 v[226:227], v[228:229], 0, s[12:13]
	s_addc_u32 s1, s39, 0
	s_add_i32 s38, s66, s43
	global_load_lds_dwordx4 v[226:227], off
	s_mov_b32 m0, s38
	s_nop 0
	global_load_lds_dwordx4 v132, s[0:1]
	s_add_i32 m0, s38, 0x2000
	s_nop 0
	global_load_lds_dwordx4 v136, s[0:1]
	v_lshl_add_u64 v[226:227], v[230:231], 0, s[12:13]
	s_mov_b32 m0, s49
	s_nop 0
	global_load_lds_dwordx4 v[226:227], off
	v_lshl_add_u64 v[226:227], v[232:233], 0, s[12:13]
	s_mov_b32 m0, s50
	s_nop 0
	global_load_lds_dwordx4 v[226:227], off
	s_waitcnt vmcnt(8)
	s_waitcnt lgkmcnt(0)
	s_setprio 3
	s_barrier
	v_mfma_f32_16x16x32_bf16 v[60:63], v[148:151], v[188:191], v[60:63]
	v_mfma_f32_16x16x32_bf16 v[56:59], v[164:167], v[188:191], v[56:59]
	v_mfma_f32_16x16x32_bf16 v[44:47], v[148:151], v[196:199], v[44:47]
	v_mfma_f32_16x16x32_bf16 v[40:43], v[164:167], v[196:199], v[40:43]
	v_mfma_f32_16x16x32_bf16 v[28:31], v[148:151], v[210:213], v[28:31]
	v_mfma_f32_16x16x32_bf16 v[24:27], v[164:167], v[210:213], v[24:27]
	v_mfma_f32_16x16x32_bf16 v[12:15], v[148:151], v[218:221], v[12:15]
	v_mfma_f32_16x16x32_bf16 v[8:11], v[164:167], v[218:221], v[8:11]
	v_mfma_f32_16x16x32_bf16 v[60:63], v[160:163], v[192:195], v[60:63]
	v_mfma_f32_16x16x32_bf16 v[56:59], v[168:171], v[192:195], v[56:59]
	v_mfma_f32_16x16x32_bf16 v[44:47], v[160:163], v[200:203], v[44:47]
	v_mfma_f32_16x16x32_bf16 v[40:43], v[168:171], v[200:203], v[40:43]
	v_mfma_f32_16x16x32_bf16 v[28:31], v[160:163], v[214:217], v[28:31]
	v_mfma_f32_16x16x32_bf16 v[24:27], v[168:171], v[214:217], v[24:27]
	v_mfma_f32_16x16x32_bf16 v[12:15], v[160:163], v[222:225], v[12:15]
	v_mfma_f32_16x16x32_bf16 v[8:11], v[168:171], v[222:225], v[8:11]
	s_setprio 0
	s_setprio 3
	v_mfma_f32_16x16x32_bf16 v[52:55], v[172:175], v[188:191], v[52:55]
	v_mfma_f32_16x16x32_bf16 v[48:51], v[180:183], v[188:191], v[48:51]
	v_mfma_f32_16x16x32_bf16 v[36:39], v[172:175], v[196:199], v[36:39]
	v_mfma_f32_16x16x32_bf16 v[32:35], v[180:183], v[196:199], v[32:35]
	v_mfma_f32_16x16x32_bf16 v[20:23], v[172:175], v[210:213], v[20:23]
	v_mfma_f32_16x16x32_bf16 v[16:19], v[180:183], v[210:213], v[16:19]
	v_mfma_f32_16x16x32_bf16 v[4:7], v[172:175], v[218:221], v[4:7]
	v_mfma_f32_16x16x32_bf16 v[0:3], v[180:183], v[218:221], v[0:3]
	v_mfma_f32_16x16x32_bf16 v[52:55], v[176:179], v[192:195], v[52:55]
	v_mfma_f32_16x16x32_bf16 v[48:51], v[184:187], v[192:195], v[48:51]
	v_mfma_f32_16x16x32_bf16 v[36:39], v[176:179], v[200:203], v[36:39]
	v_mfma_f32_16x16x32_bf16 v[32:35], v[184:187], v[200:203], v[32:35]
	v_mfma_f32_16x16x32_bf16 v[20:23], v[176:179], v[214:217], v[20:23]
	v_mfma_f32_16x16x32_bf16 v[16:19], v[184:187], v[214:217], v[16:19]
	v_mfma_f32_16x16x32_bf16 v[4:7], v[176:179], v[222:225], v[4:7]
	v_mfma_f32_16x16x32_bf16 v[0:3], v[184:187], v[222:225], v[0:3]
	s_barrier
	s_setprio 0
	s_add_u32 s36, s36, 0x100
	s_addc_u32 s37, s37, 0
	s_add_i32 s64, s64, 2
	s_add_u32 s62, s62, 0x100
	s_addc_u32 s63, s63, 0
	s_cmp_gt_u32 s64, 61
	s_cbranch_scc0 .LBB0_1813
	s_and_b64 vcc, exec, s[14:15]
	s_cbranch_vccz .LBB0_1816
	s_barrier

.LBB0_1833:
	ds_read_b128 v[24:27], v193
	ds_read_b128 v[28:31], v193 offset:1024
	ds_read_b128 v[16:19], v193 offset:2048
	ds_read_b128 v[20:23], v193 offset:3072
	ds_read_b128 v[8:11], v194
	ds_read_b128 v[12:15], v194 offset:1024
	ds_read_b128 v[0:3], v194 offset:2048
	ds_read_b128 v[4:7], v194 offset:3072
	s_add_u32 s0, s36, 0xfff80080
	s_addc_u32 s1, s37, -1
	s_cmp_eq_u32 s65, 28
	s_cselect_b32 s41, s26, s1
	s_cselect_b32 s40, s27, s0
	s_cselect_b32 s39, s17, s64
	s_cselect_b32 s38, s31, s63
	s_add_i32 m0, s35, 0xc000
	ds_read_b128 v[180:183], v195
	ds_read_b128 v[184:187], v195 offset:1024
	ds_read_b128 v[210:213], v195 offset:2048
	ds_read_b128 v[214:217], v195 offset:3072
	ds_read_b128 v[218:221], v195 offset:4096
	ds_read_b128 v[222:225], v195 offset:5120
	ds_read_b128 v[226:229], v195 offset:6144
	ds_read_b128 v[230:233], v195 offset:7168
	global_load_lds_dwordx4 v172, s[36:37]
	s_add_i32 m0, s35, 0xe000
	s_nop 0
	global_load_lds_dwordx4 v174, s[36:37]
	s_waitcnt vmcnt(8)
	s_waitcnt lgkmcnt(0)
	s_setprio 3
	s_barrier
	v_mfma_scale_f32_16x16x128_f8f6f4 v[152:155], v[24:31], v[180:187], v[152:155], v188, v188 op_sel_hi:[0,0,0]
	v_mfma_scale_f32_16x16x128_f8f6f4 v[148:151], v[16:23], v[180:187], v[148:151], v188, v188 op_sel_hi:[0,0,0]
	v_mfma_scale_f32_16x16x128_f8f6f4 v[140:143], v[24:31], v[210:217], v[140:143], v188, v188 op_sel_hi:[0,0,0]
	v_mfma_scale_f32_16x16x128_f8f6f4 v[132:135], v[16:23], v[210:217], v[132:135], v188, v188 op_sel_hi:[0,0,0]
	v_mfma_scale_f32_16x16x128_f8f6f4 v[124:127], v[24:31], v[218:225], v[124:127], v188, v188 op_sel_hi:[0,0,0]
	v_mfma_scale_f32_16x16x128_f8f6f4 v[120:123], v[16:23], v[218:225], v[120:123], v188, v188 op_sel_hi:[0,0,0]
	v_mfma_scale_f32_16x16x128_f8f6f4 v[108:111], v[24:31], v[226:233], v[108:111], v188, v188 op_sel_hi:[0,0,0]
	v_mfma_scale_f32_16x16x128_f8f6f4 v[100:103], v[16:23], v[226:233], v[100:103], v188, v188 op_sel_hi:[0,0,0]
	s_setprio 0
	s_setprio 3
	v_mfma_scale_f32_16x16x128_f8f6f4 v[156:159], v[8:15], v[180:187], v[156:159], v188, v188 op_sel_hi:[0,0,0]
	v_mfma_scale_f32_16x16x128_f8f6f4 v[144:147], v[0:7], v[180:187], v[144:147], v188, v188 op_sel_hi:[0,0,0]
	v_mfma_scale_f32_16x16x128_f8f6f4 v[136:139], v[8:15], v[210:217], v[136:139], v188, v188 op_sel_hi:[0,0,0]
	v_mfma_scale_f32_16x16x128_f8f6f4 v[128:131], v[0:7], v[210:217], v[128:131], v188, v188 op_sel_hi:[0,0,0]
	v_mfma_scale_f32_16x16x128_f8f6f4 v[116:119], v[8:15], v[218:225], v[116:119], v188, v188 op_sel_hi:[0,0,0]
	v_mfma_scale_f32_16x16x128_f8f6f4 v[112:115], v[0:7], v[218:225], v[112:115], v188, v188 op_sel_hi:[0,0,0]
	v_mfma_scale_f32_16x16x128_f8f6f4 v[104:107], v[8:15], v[226:233], v[104:107], v188, v188 op_sel_hi:[0,0,0]
	v_mfma_scale_f32_16x16x128_f8f6f4 v[96:99], v[0:7], v[226:233], v[96:99], v188, v188 op_sel_hi:[0,0,0]
	s_barrier
	s_setprio 0
	s_add_i32 s0, s56, s45
	v_lshl_add_u64 v[180:181], s[38:39], 0, v[164:165]
	s_mov_b32 m0, s0
	ds_read_b128 v[210:213], v195 offset:16384
	ds_read_b128 v[214:217], v195 offset:17408
	ds_read_b128 v[218:221], v195 offset:18432
	ds_read_b128 v[222:225], v195 offset:19456
	ds_read_b128 v[226:229], v195 offset:20480
	ds_read_b128 v[230:233], v195 offset:21504
	ds_read_b128 v[234:237], v195 offset:22528
	ds_read_b128 v[238:241], v195 offset:23552
	global_load_lds_dwordx4 v[180:181], off
	s_add_i32 m0, s0, 0x2000
	s_add_u32 s0, s38, 0x80000
	v_lshl_add_u64 v[182:183], s[38:39], 0, v[168:169]
	s_addc_u32 s1, s39, 0
	s_add_i32 s66, s57, s45
	global_load_lds_dwordx4 v[182:183], off
	s_mov_b32 m0, s66
	v_lshl_add_u64 v[186:187], s[40:41], 0, v[166:167]
	global_load_lds_dwordx4 v164, s[0:1]
	s_add_i32 m0, s66, 0x2000
	s_nop 0
	global_load_lds_dwordx4 v168, s[0:1]
	v_lshl_add_u64 v[184:185], s[40:41], 0, v[162:163]
	s_mov_b32 m0, s35
	s_nop 0
	global_load_lds_dwordx4 v[184:185], off
	s_mov_b32 m0, s46
	s_nop 0
	global_load_lds_dwordx4 v[186:187], off
	s_waitcnt vmcnt(8)
	s_waitcnt lgkmcnt(0)
	s_setprio 3
	s_barrier
	v_mfma_scale_f32_16x16x128_f8f6f4 v[92:95], v[24:31], v[210:217], v[92:95], v188, v188 op_sel_hi:[0,0,0]
	v_mfma_scale_f32_16x16x128_f8f6f4 v[88:91], v[16:23], v[210:217], v[88:91], v188, v188 op_sel_hi:[0,0,0]
	v_mfma_scale_f32_16x16x128_f8f6f4 v[76:79], v[24:31], v[218:225], v[76:79], v188, v188 op_sel_hi:[0,0,0]
	v_mfma_scale_f32_16x16x128_f8f6f4 v[68:71], v[16:23], v[218:225], v[68:71], v188, v188 op_sel_hi:[0,0,0]
	v_mfma_scale_f32_16x16x128_f8f6f4 v[60:63], v[24:31], v[226:233], v[60:63], v188, v188 op_sel_hi:[0,0,0]
	v_mfma_scale_f32_16x16x128_f8f6f4 v[56:59], v[16:23], v[226:233], v[56:59], v188, v188 op_sel_hi:[0,0,0]
	v_mfma_scale_f32_16x16x128_f8f6f4 v[44:47], v[24:31], v[234:241], v[44:47], v188, v188 op_sel_hi:[0,0,0]
	v_mfma_scale_f32_16x16x128_f8f6f4 v[40:43], v[16:23], v[234:241], v[40:43], v188, v188 op_sel_hi:[0,0,0]
	s_setprio 0
	s_setprio 3
	v_mfma_scale_f32_16x16x128_f8f6f4 v[84:87], v[8:15], v[210:217], v[84:87], v188, v188 op_sel_hi:[0,0,0]
	v_mfma_scale_f32_16x16x128_f8f6f4 v[80:83], v[0:7], v[210:217], v[80:83], v188, v188 op_sel_hi:[0,0,0]
	v_mfma_scale_f32_16x16x128_f8f6f4 v[72:75], v[8:15], v[218:225], v[72:75], v188, v188 op_sel_hi:[0,0,0]
	v_mfma_scale_f32_16x16x128_f8f6f4 v[64:67], v[0:7], v[218:225], v[64:67], v188, v188 op_sel_hi:[0,0,0]
	v_mfma_scale_f32_16x16x128_f8f6f4 v[52:55], v[8:15], v[226:233], v[52:55], v188, v188 op_sel_hi:[0,0,0]
	v_mfma_scale_f32_16x16x128_f8f6f4 v[48:51], v[0:7], v[226:233], v[48:51], v188, v188 op_sel_hi:[0,0,0]
	v_mfma_scale_f32_16x16x128_f8f6f4 v[36:39], v[8:15], v[234:241], v[36:39], v188, v188 op_sel_hi:[0,0,0]
	v_mfma_scale_f32_16x16x128_f8f6f4 v[32:35], v[0:7], v[234:241], v[32:35], v188, v188 op_sel_hi:[0,0,0]
	s_barrier
	s_setprio 0
	s_add_i32 s66, 0, 0x18000
	s_add_i32 s67, 0, 0x1c000
	v_add_u32_e32 v12, s66, v190
	v_add_u32_e32 v28, s67, v190
	ds_read_b128 v[0:3], v12
	ds_read_b128 v[4:7], v12 offset:1024
	ds_read_b128 v[8:11], v12 offset:2048
	ds_read_b128 v[12:15], v12 offset:3072
	ds_read_b128 v[16:19], v28
	ds_read_b128 v[20:23], v28 offset:1024
	ds_read_b128 v[24:27], v28 offset:2048
	ds_read_b128 v[28:31], v28 offset:3072
	s_add_u32 s0, s40, 0x80000
	s_addc_u32 s1, s41, 0
	s_mov_b32 m0, s47
	ds_read_b128 v[210:213], v195 offset:32768
	ds_read_b128 v[214:217], v195 offset:33792
	ds_read_b128 v[218:221], v195 offset:34816
	ds_read_b128 v[222:225], v195 offset:35840
	ds_read_b128 v[226:229], v195 offset:36864
	ds_read_b128 v[230:233], v195 offset:37888
	ds_read_b128 v[234:237], v195 offset:38912
	ds_read_b128 v[238:241], v195 offset:39936
	global_load_lds_dwordx4 v162, s[0:1]
	s_mov_b32 m0, s48
	s_nop 0
	global_load_lds_dwordx4 v166, s[0:1]
	s_waitcnt vmcnt(8)
	s_waitcnt lgkmcnt(0)
	s_setprio 3
	s_barrier
	v_mfma_scale_f32_16x16x128_f8f6f4 v[152:155], v[0:7], v[210:217], v[152:155], v188, v188 op_sel_hi:[0,0,0]
	v_mfma_scale_f32_16x16x128_f8f6f4 v[148:151], v[8:15], v[210:217], v[148:151], v188, v188 op_sel_hi:[0,0,0]
	v_mfma_scale_f32_16x16x128_f8f6f4 v[140:143], v[0:7], v[218:225], v[140:143], v188, v188 op_sel_hi:[0,0,0]
	v_mfma_scale_f32_16x16x128_f8f6f4 v[132:135], v[8:15], v[218:225], v[132:135], v188, v188 op_sel_hi:[0,0,0]
	v_mfma_scale_f32_16x16x128_f8f6f4 v[124:127], v[0:7], v[226:233], v[124:127], v188, v188 op_sel_hi:[0,0,0]
	v_mfma_scale_f32_16x16x128_f8f6f4 v[120:123], v[8:15], v[226:233], v[120:123], v188, v188 op_sel_hi:[0,0,0]
	v_mfma_scale_f32_16x16x128_f8f6f4 v[108:111], v[0:7], v[234:241], v[108:111], v188, v188 op_sel_hi:[0,0,0]
	v_mfma_scale_f32_16x16x128_f8f6f4 v[100:103], v[8:15], v[234:241], v[100:103], v188, v188 op_sel_hi:[0,0,0]
	s_setprio 0
	s_setprio 3
	v_mfma_scale_f32_16x16x128_f8f6f4 v[156:159], v[16:23], v[210:217], v[156:159], v188, v188 op_sel_hi:[0,0,0]
	v_mfma_scale_f32_16x16x128_f8f6f4 v[144:147], v[24:31], v[210:217], v[144:147], v188, v188 op_sel_hi:[0,0,0]
	v_mfma_scale_f32_16x16x128_f8f6f4 v[136:139], v[16:23], v[218:225], v[136:139], v188, v188 op_sel_hi:[0,0,0]
	v_mfma_scale_f32_16x16x128_f8f6f4 v[128:131], v[24:31], v[218:225], v[128:131], v188, v188 op_sel_hi:[0,0,0]
	v_mfma_scale_f32_16x16x128_f8f6f4 v[116:119], v[16:23], v[226:233], v[116:119], v188, v188 op_sel_hi:[0,0,0]
	v_mfma_scale_f32_16x16x128_f8f6f4 v[112:115], v[24:31], v[226:233], v[112:115], v188, v188 op_sel_hi:[0,0,0]
	v_mfma_scale_f32_16x16x128_f8f6f4 v[104:107], v[16:23], v[234:241], v[104:107], v188, v188 op_sel_hi:[0,0,0]
	v_mfma_scale_f32_16x16x128_f8f6f4 v[96:99], v[24:31], v[234:241], v[96:99], v188, v188 op_sel_hi:[0,0,0]
	s_barrier
	s_setprio 0
	s_add_i32 s0, s66, s45
	v_lshl_add_u64 v[180:181], v[180:181], 0, s[12:13]
	s_mov_b32 m0, s0
	ds_read_b128 v[210:213], v195 offset:49152
	ds_read_b128 v[214:217], v195 offset:50176
	ds_read_b128 v[218:221], v195 offset:51200
	ds_read_b128 v[222:225], v195 offset:52224
	ds_read_b128 v[226:229], v195 offset:53248
	ds_read_b128 v[230:233], v195 offset:54272
	ds_read_b128 v[234:237], v195 offset:55296
	ds_read_b128 v[238:241], v195 offset:56320
	global_load_lds_dwordx4 v[180:181], off
	s_add_i32 m0, s0, 0x2000
	s_add_u32 s0, s38, 0x80080
	v_lshl_add_u64 v[180:181], v[182:183], 0, s[12:13]
	s_addc_u32 s1, s39, 0
	s_add_i32 s38, s67, s45
	global_load_lds_dwordx4 v[180:181], off
	s_mov_b32 m0, s38
	s_nop 0
	global_load_lds_dwordx4 v164, s[0:1]
	s_add_i32 m0, s38, 0x2000
	s_nop 0
	global_load_lds_dwordx4 v168, s[0:1]
	v_lshl_add_u64 v[180:181], v[184:185], 0, s[12:13]
	s_mov_b32 m0, s51
	s_nop 0
	global_load_lds_dwordx4 v[180:181], off
	v_lshl_add_u64 v[180:181], v[186:187], 0, s[12:13]
	s_mov_b32 m0, s52
	s_nop 0
	global_load_lds_dwordx4 v[180:181], off
	s_waitcnt vmcnt(8)
	s_waitcnt lgkmcnt(0)
	s_setprio 3
	s_barrier
	v_mfma_scale_f32_16x16x128_f8f6f4 v[92:95], v[0:7], v[210:217], v[92:95], v188, v188 op_sel_hi:[0,0,0]
	v_mfma_scale_f32_16x16x128_f8f6f4 v[88:91], v[8:15], v[210:217], v[88:91], v188, v188 op_sel_hi:[0,0,0]
	v_mfma_scale_f32_16x16x128_f8f6f4 v[76:79], v[0:7], v[218:225], v[76:79], v188, v188 op_sel_hi:[0,0,0]
	v_mfma_scale_f32_16x16x128_f8f6f4 v[68:71], v[8:15], v[218:225], v[68:71], v188, v188 op_sel_hi:[0,0,0]
	v_mfma_scale_f32_16x16x128_f8f6f4 v[60:63], v[0:7], v[226:233], v[60:63], v188, v188 op_sel_hi:[0,0,0]
	v_mfma_scale_f32_16x16x128_f8f6f4 v[56:59], v[8:15], v[226:233], v[56:59], v188, v188 op_sel_hi:[0,0,0]
	v_mfma_scale_f32_16x16x128_f8f6f4 v[44:47], v[0:7], v[234:241], v[44:47], v188, v188 op_sel_hi:[0,0,0]
	v_mfma_scale_f32_16x16x128_f8f6f4 v[40:43], v[8:15], v[234:241], v[40:43], v188, v188 op_sel_hi:[0,0,0]
	s_setprio 0
	s_setprio 3
	v_mfma_scale_f32_16x16x128_f8f6f4 v[84:87], v[16:23], v[210:217], v[84:87], v188, v188 op_sel_hi:[0,0,0]
	v_mfma_scale_f32_16x16x128_f8f6f4 v[80:83], v[24:31], v[210:217], v[80:83], v188, v188 op_sel_hi:[0,0,0]
	v_mfma_scale_f32_16x16x128_f8f6f4 v[72:75], v[16:23], v[218:225], v[72:75], v188, v188 op_sel_hi:[0,0,0]
	v_mfma_scale_f32_16x16x128_f8f6f4 v[64:67], v[24:31], v[218:225], v[64:67], v188, v188 op_sel_hi:[0,0,0]
	v_mfma_scale_f32_16x16x128_f8f6f4 v[52:55], v[16:23], v[226:233], v[52:55], v188, v188 op_sel_hi:[0,0,0]
	v_mfma_scale_f32_16x16x128_f8f6f4 v[48:51], v[24:31], v[226:233], v[48:51], v188, v188 op_sel_hi:[0,0,0]
	v_mfma_scale_f32_16x16x128_f8f6f4 v[36:39], v[16:23], v[234:241], v[36:39], v188, v188 op_sel_hi:[0,0,0]
	v_mfma_scale_f32_16x16x128_f8f6f4 v[32:35], v[24:31], v[234:241], v[32:35], v188, v188 op_sel_hi:[0,0,0]
	s_barrier
	s_setprio 0
	s_add_u32 s36, s36, 0x100
	s_addc_u32 s37, s37, 0
	s_add_i32 s65, s65, 2
	s_add_u32 s63, s63, 0x100
	s_addc_u32 s64, s64, 0
	s_cmp_gt_u32 s65, 29
	s_cbranch_scc0 .LBB0_1833
	s_and_b64 vcc, exec, s[14:15]
	s_cbranch_vccz .LBB0_1836
	s_barrier
